# QKV GEMM epilogue: all 8 rope-table loads hoisted to the epilogue top (spare fragment registers) with counted vmcnt so they no longer wait on the preceding stores; plus earlier elementwise-loop prefet
# speedup vs baseline: 1.0047x; 1.0047x over previous
; #define LAS __attribute__((address_space(3)))
; __global__ void __launch_bounds__(512, 2) mega(Params p, int ph_lo, int ph_hi) {
;     ...
;             LAS unsigned char* QT = lds; LAS unsigned char* AI = lds + 17408; LAS unsigned char* VS = lds + 2 * 17408; LAS unsigned char* BI = lds + 3 * 17408;
;             LAS unsigned char* SC = BI + 160 * HP * 2; LAS float* EX = (LAS float*)(SC + 8 * 2304); LAS float* SSQ = EX + 1024;
;             const int k = tid & 127, I = tid >> 7;
;             const int fr = lane & 15, fq = lane >> 4;
;             const int wI = wave & 3, vh = wave >> 2;
;             for (int unit = bid; unit < 2048; unit += G) {
;                 const int c = unit & 127, bh = unit >> 7, h = bh & 7, b = bh >> 3;
;                 const size_t row0 = (size_t)b * SEQ + c * 64;
;                 const int chn = h * 128 + k;
;     ...
;                 const int offBI = 8 * wI * (wI + 1);
; #pragma unroll
;                 for (int J = 0; J < 4; ++J) {
;                     u32x2 w = {0u, 0u};
;                     if (J <= wI) {
;                         f32x4 sacc = {0.f, 0.f, 0.f, 0.f};
; #pragma unroll
;                         for (int kq = 0; kq < 4; ++kq) {
;                             const bf16x8 a = *(const LAS bf16x8*)(BI + ((offBI + 16 * J + fr) * HP + 32 * kq + 8 * fq) * 2);
;                             const bf16x8 bq = *(const LAS bf16x8*)(AI + ((16 * wI + fr) * HP + 32 * kq + 8 * fq) * 2);
;                             sacc = __builtin_amdgcn_mfma_f32_16x16x32_bf16(a, bq, sacc, 0, 0, 0);
;                         }
; #pragma unroll
;                         for (int j = 0; j < 4; ++j) if (16 * J + 4 * fq + j > 16 * wI + fr) sacc[j] = 0.f;
.LBB0_412:
	s_and_b32 s0, s93, 0xffffffc0
	v_writelane_b32 v253, s93, 17
	s_cmpk_gt_i32 s2, 0x7ff
	v_writelane_b32 v253, s0, 18
	v_mbcnt_lo_u32_b32 v0, -1, 0
	v_mbcnt_hi_u32_b32 v0, -1, v0
	s_waitcnt vmcnt(0) lgkmcnt(0)
	s_barrier
	s_cbranch_scc1 .LBB0_551
	v_readlane_b32 s1, v253, 17
	s_bfe_u32 s3, s1, 0x20006
	s_lshl_b32 s4, s3, 6
	v_readlane_b32 s0, v253, 18
	s_add_i32 s4, s4, 0
	s_add_i32 s4, s4, 0x1ce00
	v_add_u32_e32 v1, s0, v0
	s_lshr_b32 s0, s1, 2
	s_and_b32 s1, s1, 0xffffff00
	v_and_b32_e32 v93, 0x7f, v1
	s_and_b32 s33, s0, 0x3fffffc0
	s_mul_i32 s0, s96, 0x900
	s_add_i32 s5, s4, s1
	v_ashrrev_i32_e32 v8, 4, v0
	s_add_i32 s1, 0, 0x1be00
	s_add_i32 s52, s0, 0
	s_add_i32 s0, s3, 1
	v_lshlrev_b32_e32 v6, 3, v8
	v_lshlrev_b32_e32 v10, 2, v8
	v_and_b32_e32 v8, 0x3fffff80, v1
	v_lshl_add_u32 v117, v93, 2, s1
	s_mul_i32 s0, s3, s0
	v_and_b32_e32 v9, 15, v0
	v_lshl_add_u32 v118, v8, 2, v117
	v_and_b32_e32 v8, -16, v0
	v_lshlrev_b32_e32 v4, 3, v0
	v_lshl_add_u32 v116, v1, 2, s1
	v_lshl_add_u32 v13, s0, 3, v9
	s_movk_i32 s39, 0x88
	v_add_u32_e32 v16, 0, v8
	v_bfe_u32 v8, v0, 2, 2
	v_lshlrev_b32_e32 v19, 2, v0
	v_cmp_gt_u32_e64 s[0:1], 16, v0
	v_ashrrev_i32_e32 v96, 4, v1
	v_add_u32_e32 v0, 0x200, v1
	v_and_b32_e32 v4, 0x78, v4
	v_ashrrev_i32_e32 v98, 4, v0
	v_mul_lo_u32 v0, v96, s39
	v_ashrrev_i32_e32 v5, 7, v1
	v_or_b32_e32 v18, v6, v8
	v_and_or_b32 v8, v19, 12, s33
	v_add_u32_e32 v119, s5, v19
	v_add_lshl_u32 v19, v0, v4, 1
	v_mul_lo_u32 v0, v98, s39
	s_movk_i32 s10, 0x880
	v_add_lshl_u32 v20, v0, v4, 1
	v_mul_lo_u32 v0, v5, s10
	v_or_b32_e32 v0, v0, v93
	v_lshlrev_b32_e32 v121, 1, v0
	v_mul_u32_u24_e32 v0, 0x88, v13
	v_lshl_or_b32 v92, s3, 4, v9
	v_add_lshl_u32 v122, v6, v0, 1
	v_or_b32_e32 v0, 3, v10
	v_cmp_gt_i32_e64 s[18:19], v0, v92
	v_or_b32_e32 v0, 2, v10
	v_cmp_gt_i32_e64 s[20:21], v0, v92
	v_add_u32_e32 v0, 16, v10
	v_cmp_gt_i32_e64 s[26:27], v0, v92
	v_add_u32_e32 v0, 17, v10
	v_cmp_gt_i32_e64 s[28:29], v0, v92
	v_add_u32_e32 v0, 18, v10
	v_cmp_gt_i32_e64 s[30:31], v0, v92
	v_add_u32_e32 v0, 19, v10
	v_cmp_gt_i32_e64 s[34:35], v0, v92
	v_add_u32_e32 v0, 32, v10
	v_cmp_gt_i32_e64 s[40:41], v0, v92
	v_add_u32_e32 v0, 33, v10
	v_cmp_gt_i32_e64 s[68:69], v0, v92
	v_writelane_b32 v253, s40, 19
	v_add_u32_e32 v0, 34, v10
	s_add_i32 s52, s52, 0x17600
	v_writelane_b32 v253, s41, 20
	v_cmp_gt_i32_e64 s[40:41], v0, v92
	v_add_u32_e32 v0, 35, v10
	v_cmp_gt_i32_e64 s[42:43], v0, v92
	v_add_u32_e32 v0, 48, v10
	s_cmp_lg_u32 s3, 0
	v_cmp_gt_i32_e64 s[44:45], v0, v92
	v_add_u32_e32 v0, 49, v10
	s_cselect_b64 s[78:79], -1, 0
	s_cmp_gt_u32 s3, 1
	v_cmp_gt_i32_e64 s[46:47], v0, v92
	v_add_u32_e32 v0, 50, v10
	s_cselect_b64 s[80:81], -1, 0
	s_cmp_eq_u32 s3, 3
	v_cmp_gt_i32_e64 s[48:49], v0, v92
	v_add_u32_e32 v0, 51, v10
	v_mov_b32_e32 v2, s84
	v_mov_b32_e32 v3, s85
	s_cselect_b64 s[84:85], -1, 0
	v_cmp_gt_i32_e64 s[50:51], v0, v92
	v_mad_u64_u32 v[0:1], s[66:67], v18, s39, v[8:9]
	s_add_i32 s3, 0, 0x8800
	v_mov_b32_e32 v91, 0
	v_lshl_add_u32 v123, v0, 1, s3
	s_ashr_i32 s3, s2, 31
	v_or_b32_e32 v90, s33, v9
	s_lshl_b64 s[66:67], s[2:3], 15
	v_lshlrev_b64 v[0:1], 8, v[90:91]
	v_ashrrev_i32_e32 v7, 31, v6
	v_lshl_add_u64 v[0:1], s[66:67], 0, v[0:1]
	v_lshl_add_u64 v[0:1], v[6:7], 1, v[0:1]
	v_add_u32_e32 v94, s33, v10
	v_mul_u32_u24_e32 v14, 0x88, v92
	v_mul_u32_u24_e32 v17, 0x48, v9
	v_lshl_add_u64 v[0:1], s[88:89], 0, v[0:1]
	s_mov_b64 s[66:67], 0x30c0
	v_lshlrev_b32_e32 v88, 4, v5
	v_mul_u32_u24_e32 v11, 0x90, v9
	v_add_u32_e32 v12, s52, v6
	v_mul_u32_u24_e32 v15, 0x110, v92
	v_lshl_add_u32 v120, v9, 2, s4
	v_ashrrev_i32_e32 v95, 31, v94
	v_cmp_eq_u32_e64 s[4:5], 1, v5
	v_cmp_eq_u32_e64 s[6:7], 2, v5
	v_cmp_eq_u32_e64 s[8:9], 3, v5
	v_cmp_gt_i32_e64 s[10:11], 1, v5
	v_cmp_gt_i32_e64 s[12:13], 2, v5
	v_add_u32_e32 v21, 0x1100, v121
	v_cmp_gt_i32_e64 s[14:15], 3, v5
	v_add_u32_e32 v22, 0x3300, v121
	v_cmp_gt_i32_e64 s[16:17], 4, v5
	v_add_u32_e32 v5, 0x6600, v121
	v_add_u32_e32 v23, 0x110, v121
	v_add_u32_e32 v24, 0x1210, v121
	v_add_u32_e32 v25, 0x3410, v121
	v_add_u32_e32 v26, 0x6710, v121
	v_add_u32_e32 v27, 0x220, v121
	v_add_u32_e32 v28, 0x1320, v121
	v_add_u32_e32 v29, 0x3520, v121
	v_add_u32_e32 v30, 0x6820, v121
	v_add_u32_e32 v31, 0x330, v121
	v_add_u32_e32 v32, 0x1430, v121
	v_add_u32_e32 v33, 0x3630, v121
	v_add_u32_e32 v34, 0x6930, v121
	v_add_u32_e32 v35, 0x440, v121
	v_add_u32_e32 v36, 0x1540, v121
	v_add_u32_e32 v37, 0x3740, v121
	v_add_u32_e32 v38, 0x6a40, v121
	v_add_u32_e32 v39, 0x550, v121
	v_add_u32_e32 v40, 0x1650, v121
	v_add_u32_e32 v41, 0x3850, v121
	v_add_u32_e32 v42, 0x6b50, v121
	v_add_u32_e32 v43, 0x660, v121
	v_add_u32_e32 v44, 0x1760, v121
; #define LAS __attribute__((address_space(3)))
; __global__ void __launch_bounds__(512, 2) mega(Params p, int ph_lo, int ph_hi) {
;     ...
;             LAS unsigned char* QT = lds; LAS unsigned char* AI = lds + 17408; LAS unsigned char* VS = lds + 2 * 17408; LAS unsigned char* BI = lds + 3 * 17408;
;             LAS unsigned char* SC = BI + 160 * HP * 2; LAS float* EX = (LAS float*)(SC + 8 * 2304); LAS float* SSQ = EX + 1024;
;             const int k = tid & 127, I = tid >> 7;
;             const int fr = lane & 15, fq = lane >> 4;
;             const int wI = wave & 3, vh = wave >> 2;
;             for (int unit = bid; unit < 2048; unit += G) {
;                 const int c = unit & 127, bh = unit >> 7, h = bh & 7, b = bh >> 3;
;                 const size_t row0 = (size_t)b * SEQ + c * 64;
;                 const int chn = h * 128 + k;
;                 const float l0 = p.lb_logits[chn], l1 = p.lb_logits[1024 + chn], l2 = p.lb_logits[2048 + chn];
;                 bf16_t fzr[16], qr[16];
; #pragma unroll
;                 for (int i = 0; i < 16; ++i) { fzr[i] = BIG[(row0 + 16 * I + i) * INC + 3072 + chn]; qr[i] = BIG[(row0 + 16 * I + i) * INC + 2048 + chn]; }
;                 u32x4 vst[2];
; #pragma unroll
;                 for (int i = 0; i < 2; ++i) { const int idx = tid + 512 * i, r = idx >> 4, ch = idx & 15; vst[i] = *(const u32x4*)(BIG + (row0 + r) * INC + 4096 + h * 128 + 8 * ch); }
	v_add_u32_e32 v45, 0x3960, v121
	v_add_u32_e32 v46, 0x6c60, v121
	v_add_u32_e32 v47, 0x770, v121
	v_add_u32_e32 v48, 0x1870, v121
	v_add_u32_e32 v49, 0x3a70, v121
	v_add_u32_e32 v50, 0x6d70, v121
	v_add_u32_e32 v51, 0x880, v121
	v_add_u32_e32 v52, 0x1980, v121
	v_add_u32_e32 v53, 0x3b80, v121
	v_add_u32_e32 v54, 0x6e80, v121
	v_add_u32_e32 v55, 0x990, v121
	v_add_u32_e32 v56, 0x1a90, v121
	v_add_u32_e32 v57, 0x3c90, v121
	v_add_u32_e32 v58, 0x6f90, v121
	v_add_u32_e32 v59, 0xaa0, v121
	v_add_u32_e32 v60, 0x1ba0, v121
	v_add_u32_e32 v61, 0x3da0, v121
	v_add_u32_e32 v62, 0x70a0, v121
	v_add_u32_e32 v63, 0xbb0, v121
	v_add_u32_e32 v64, 0x1cb0, v121
	v_add_u32_e32 v65, 0x3eb0, v121
	v_add_u32_e32 v66, 0x71b0, v121
	v_add_u32_e32 v67, 0xcc0, v121
	v_add_u32_e32 v68, 0x1dc0, v121
	v_add_u32_e32 v69, 0x3fc0, v121
	v_add_u32_e32 v70, 0x72c0, v121
	v_add_u32_e32 v71, 0xdd0, v121
	v_add_u32_e32 v72, 0x1ed0, v121
	v_add_u32_e32 v73, 0x40d0, v121
	v_add_u32_e32 v74, 0x73d0, v121
	v_add_u32_e32 v75, 0xee0, v121
	v_add_u32_e32 v76, 0x1fe0, v121
	v_add_u32_e32 v77, 0x41e0, v121
	v_add_u32_e32 v78, 0x74e0, v121
	v_add_u32_e32 v79, 0xff0, v121
	v_add_u32_e32 v80, 0x20f0, v121
	v_add_u32_e32 v81, 0x42f0, v121
	v_add_u32_e32 v82, 0x75f0, v121
	v_add_lshl_u32 v13, v6, v14, 1
	v_cmp_lt_i32_e64 s[22:23], v10, v92
	v_cmp_gt_i32_e64 s[24:25], v10, v92
	v_add_u32_e32 v14, 0x1100, v122
	v_add_u32_e32 v83, 0x2200, v122
	v_add_u32_e32 v84, 0x3300, v122
	v_add_lshl_u32 v10, v6, v17, 1
	v_lshl_add_u64 v[102:103], v[0:1], 0, s[66:67]
	s_ashr_i32 s95, s94, 31
	v_mbcnt_lo_u32_b32 v0, -1, 0
	s_mov_b32 s75, 0
	v_ashrrev_i32_e32 v89, 31, v88
	v_ashrrev_i32_e32 v97, 31, v96
	v_ashrrev_i32_e32 v99, 31, v98
	v_add_u32_e32 v124, 0x2200, v123
	v_lshl_add_u64 v[100:101], v[94:95], 2, v[2:3]
	s_lshl_b64 s[86:87], s[94:95], 15
	s_lshl_b32 s3, s2, 6
	s_lshl_b32 s55, s94, 6
	s_movk_i32 s93, 0x2000
	s_movk_i32 s95, 0x3000
	v_lshlrev_b32_e32 v104, 1, v4
	s_mov_b32 s97, 0x800000
	s_mov_b32 s39, 0x3f317217
	s_mov_b32 s33, 0x7f800000
	v_add_u32_e32 v125, 0, v19
	v_add_u32_e32 v126, 0, v20
	v_add_u32_e32 v127, 0, v21
	v_add_u32_e32 v128, 0, v22
	v_add_u32_e32 v129, 0, v5
	v_add_u32_e32 v130, 0, v24
	v_add_u32_e32 v131, 0, v25
	v_add_u32_e32 v132, 0, v26
	v_add_u32_e32 v133, 0, v28
	v_add_u32_e32 v134, 0, v29
	v_add_u32_e32 v135, 0, v30
	v_add_u32_e32 v136, 0, v32
	v_add_u32_e32 v137, 0, v33
	v_add_u32_e32 v138, 0, v34
	v_add_u32_e32 v139, 0, v36
	v_add_u32_e32 v140, 0, v37
	v_add_u32_e32 v141, 0, v38
	v_add_u32_e32 v142, 0, v40
	v_add_u32_e32 v143, 0, v41
	v_add_u32_e32 v144, 0, v42
	v_add_u32_e32 v145, 0, v44
	v_add_u32_e32 v146, 0, v45
	v_add_u32_e32 v147, 0, v46
	v_add_u32_e32 v148, 0, v48
	v_add_u32_e32 v149, 0, v49
	v_add_u32_e32 v150, 0, v50
	v_add_u32_e32 v151, 0, v52
	v_add_u32_e32 v152, 0, v53
	v_add_u32_e32 v153, 0, v54
	v_add_u32_e32 v154, 0, v56
	v_add_u32_e32 v155, 0, v57
	v_add_u32_e32 v156, 0, v58
	v_add_u32_e32 v157, 0, v60
	v_add_u32_e32 v158, 0, v61
	v_add_u32_e32 v159, 0, v62
	v_add_u32_e32 v160, 0, v64
	v_add_u32_e32 v161, 0, v65
	v_add_u32_e32 v162, 0, v66
	v_add_u32_e32 v163, 0, v68
	v_add_u32_e32 v164, 0, v69
	v_add_u32_e32 v165, 0, v70
	v_add_u32_e32 v166, 0, v72
	v_add_u32_e32 v167, 0, v73
	v_add_u32_e32 v168, 0, v74
	v_add_u32_e32 v169, 0, v76
	v_add_u32_e32 v170, 0, v77
	v_add_u32_e32 v171, 0, v78
	v_add_u32_e32 v172, 0, v80
	v_add_u32_e32 v173, 0, v81
	v_add_u32_e32 v174, 0, v82
	v_add_u32_e32 v175, 0, v14
	v_add_u32_e32 v176, 0, v83
	v_add_u32_e32 v177, 0, v84
	v_add_u32_e32 v178, v16, v15
	v_add_u32_e32 v179, s52, v10
	v_mbcnt_hi_u32_b32 v180, -1, v0
	v_mov_b32_e32 v181, 0x358637bd
	v_mov_b32_e32 v182, 0x260
	v_mov_b32_e32 v183, 0x3000
	v_mov_b32_e32 v184, 0x41b17218
	v_add_u32_e32 v185, 0, v23
	v_add_u32_e32 v186, 0, v27
	v_add_u32_e32 v187, 0, v31
	v_add_u32_e32 v188, 0, v35
	v_add_u32_e32 v189, 0, v39
	v_add_u32_e32 v190, 0, v43
	v_add_u32_e32 v191, 0, v47
	v_add_u32_e32 v192, 0, v51
	v_add_u32_e32 v193, 0, v55
	v_add_u32_e32 v194, 0, v59
	v_add_u32_e32 v195, 0, v63
	v_add_u32_e32 v196, 0, v67
	v_add_u32_e32 v197, 0, v71
	v_add_u32_e32 v198, 0, v75
	v_add_u32_e32 v199, 0, v79
	v_add_u32_e32 v200, 0, v13
	v_add_u32_e32 v201, v12, v11
	v_mbcnt_lo_u32_b32 v254, -1, 0
	v_mbcnt_hi_u32_b32 v254, -1, v254
	s_lshl_b32 s98, s96, 6
	s_movk_i32 s99, 0x3000
	v_add_u32_e32 v254, s98, v254
	v_lshrrev_b32_e32 v255, 7, v254
	v_lshlrev_b32_e32 v255, 11, v255
	v_add_u32_e32 v255, 0x1000, v255
	v_bfe_u32 v252, v254, 1, 6
	v_mad_u32_u24 v255, v252, s99, v255
	v_and_b32_e32 v252, 1, v254
	v_lshl_add_u32 v255, v252, 7, v255
	v_lshlrev_b32_e32 v252, 7, v254
	v_mov_b32_e32 v254, v255
	s_mov_b32 s66, s2
	s_branch .LBB0_415

; __global__ void __launch_bounds__(512, 2) mega(Params p, int ph_lo, int ph_hi) {
;     ...
;             for (int unit = bid; unit < 2048; unit += G) {
;                 const int c = unit & 127, bh = unit >> 7, h = bh & 7, b = bh >> 3;
;                 const size_t row0 = (size_t)b * SEQ + c * 64;
;                 const int chn = h * 128 + k;
;                 const float l0 = p.lb_logits[chn], l1 = p.lb_logits[1024 + chn], l2 = p.lb_logits[2048 + chn];
;                 bf16_t fzr[16], qr[16];
; #pragma unroll
;                 for (int i = 0; i < 16; ++i) { fzr[i] = BIG[(row0 + 16 * I + i) * INC + 3072 + chn]; qr[i] = BIG[(row0 + 16 * I + i) * INC + 2048 + chn]; }
;                 u32x4 vst[2];
; #pragma unroll
;                 for (int i = 0; i < 2; ++i) { const int idx = tid + 512 * i, r = idx >> 4, ch = idx & 15; vst[i] = *(const u32x4*)(BIG + (row0 + r) * INC + 4096 + h * 128 + 8 * ch); }
;                 bf16x8 sin[4][4];
; #pragma unroll
;                 for (int kq = 0; kq < 4; ++kq)
; #pragma unroll
;                     for (int vt = 0; vt < 4; ++vt) sin[kq][vt] = *(const bf16x8*)(SSTB + ((size_t)unit * 128 + 64 * vh + 16 * vt + fr) * 128 + 32 * kq + 8 * fq);
;                 const size_t orow = row0 + 16 * wI + fr;
;                 u32x2 graw[4]; f32x4 gnv[4];
; #pragma unroll
;                 for (int vt = 0; vt < 4; ++vt) { const int v = 64 * vh + 16 * vt + 4 * fq; graw[vt] = *(const u32x2*)(BIG + orow * INC + 5120 + h * 128 + v); gnv[vt] = *(const f32x4*)(p.g_norm + h * 128 + v); }
.LBB0_415:
	s_and_b32 s67, s66, 0x380
	v_or_b32_e32 v6, s67, v93
	s_ashr_i32 s52, s66, 10
	v_lshlrev_b32_e32 v90, 2, v6
	s_ashr_i32 s53, s52, 31
	v_lshl_add_u64 v[0:1], s[82:83], 0, v[90:91]
	s_lshl_b64 s[52:53], s[52:53], 13
	s_and_b32 s74, s3, 0x1fc0
	v_add_co_u32_e32 v0, vcc, s93, v0
	s_or_b32 s52, s52, s74
	s_nop 0
	v_addc_co_u32_e32 v1, vcc, 0, v1, vcc
	global_load_dword v228, v90, s[82:83]
	global_load_dword v234, v[0:1], off offset:-4096
	global_load_dword v246, v[0:1], off
	v_lshl_add_u64 v[0:1], s[52:53], 0, v[88:89]
	v_mov_b64_e32 v[2:3], s[72:73]
	v_mad_u64_u32 v[4:5], vcc, v0, s95, v[2:3]
	v_mad_i32_i24 v5, v1, s95, v5
	v_lshlrev_b32_e32 v90, 1, v6
	v_lshl_add_u64 v[202:203], v[4:5], 0, v[90:91]
	s_movk_i32 s74, 0x4000
	v_add_co_u32_e32 v204, vcc, s74, v202
	s_movk_i32 s74, 0x7000
	s_nop 0
	v_addc_co_u32_e32 v205, vcc, 0, v203, vcc
	v_add_co_u32_e32 v206, vcc, s74, v202
	s_mov_b32 s74, 0xa000
	s_nop 0
	v_addc_co_u32_e32 v207, vcc, 0, v203, vcc
	v_add_co_u32_e32 v208, vcc, s74, v202
	s_mov_b32 s74, 0xd000
	s_nop 0
	v_addc_co_u32_e32 v209, vcc, 0, v203, vcc
	v_add_co_u32_e32 v210, vcc, s74, v202
	s_mov_b32 s74, 0x10000
	s_nop 0
	v_addc_co_u32_e32 v211, vcc, 0, v203, vcc
	v_add_co_u32_e32 v214, vcc, s74, v202
	s_mov_b32 s74, 0x13000
	s_nop 0
	v_addc_co_u32_e32 v215, vcc, 0, v203, vcc
	v_add_co_u32_e32 v218, vcc, s74, v202
	s_mov_b32 s74, 0x16000
	s_nop 0
	v_addc_co_u32_e32 v219, vcc, 0, v203, vcc
	v_add_co_u32_e32 v224, vcc, s74, v202
	s_mov_b32 s74, 0x19000
	s_nop 0
	v_addc_co_u32_e32 v225, vcc, 0, v203, vcc
	v_add_co_u32_e32 v220, vcc, s74, v202
	s_mov_b32 s74, 0x1c000
	s_nop 0
	v_addc_co_u32_e32 v221, vcc, 0, v203, vcc
	v_add_co_u32_e32 v226, vcc, s74, v202
	s_mov_b32 s74, 0x1f000
	s_nop 0
	v_addc_co_u32_e32 v227, vcc, 0, v203, vcc
	v_add_co_u32_e32 v230, vcc, s74, v202
	s_mov_b32 s74, 0x22000
	s_nop 0
	v_addc_co_u32_e32 v231, vcc, 0, v203, vcc
	v_add_co_u32_e32 v232, vcc, s74, v202
	s_mov_b32 s74, 0x25000
	s_nop 0
	v_addc_co_u32_e32 v233, vcc, 0, v203, vcc
	v_add_co_u32_e32 v236, vcc, s74, v202
	s_mov_b32 s74, 0x28000
	s_nop 0
	v_addc_co_u32_e32 v237, vcc, 0, v203, vcc
	v_add_co_u32_e32 v238, vcc, s74, v202
	s_mov_b32 s74, 0x2b000
	s_nop 0
	v_addc_co_u32_e32 v239, vcc, 0, v203, vcc
	v_add_co_u32_e32 v240, vcc, s74, v202
	s_mov_b32 s74, 0x2e000
	s_nop 0
	v_addc_co_u32_e32 v241, vcc, 0, v203, vcc
	v_add_co_u32_e32 v242, vcc, s74, v202
	v_lshl_add_u64 v[0:1], s[52:53], 0, v[96:97]
	s_nop 0
	v_addc_co_u32_e32 v243, vcc, 0, v203, vcc
	v_mad_u64_u32 v[4:5], vcc, v0, s95, v[2:3]
	v_mad_i32_i24 v5, v1, s95, v5
	s_lshl_b32 s74, s67, 1
	v_lshl_add_u64 v[0:1], v[4:5], 0, s[74:75]
	v_mov_b32_e32 v105, v91
	v_lshl_add_u64 v[0:1], v[0:1], 0, v[104:105]
	v_add_co_u32_e32 v0, vcc, s93, v0
	v_lshl_add_u64 v[4:5], s[52:53], 0, v[98:99]
	s_nop 0
	v_addc_co_u32_e32 v1, vcc, 0, v1, vcc
	v_mad_u64_u32 v[6:7], vcc, v4, s95, v[2:3]
	v_mad_i32_i24 v7, v5, s95, v7
	v_lshl_add_u64 v[4:5], v[6:7], 0, s[74:75]
	v_lshl_add_u64 v[4:5], v[4:5], 0, v[104:105]
	v_add_co_u32_e32 v4, vcc, s93, v4
	v_or_b32_e32 v114, s52, v92
	s_nop 0
	v_addc_co_u32_e32 v5, vcc, 0, v5, vcc
	s_movk_i32 vcc_lo, 0xd000
	global_load_dwordx4 v[80:83], v[0:1], off
	global_load_dwordx4 v[84:87], v[4:5], off
	v_add_co_u32_e32 v0, vcc, vcc_lo, v102
	s_movk_i32 s52, 0x1000
	s_nop 0
	v_addc_co_u32_e32 v1, vcc, -1, v103, vcc
	s_movk_i32 vcc_lo, 0xe000
	s_nop 0
	v_add_co_u32_e32 v4, vcc, vcc_lo, v102
	v_mov_b32_e32 v115, s53
	s_nop 0
	v_addc_co_u32_e32 v5, vcc, -1, v103, vcc
	s_movk_i32 vcc_lo, 0xf000
	s_nop 0
	v_add_co_u32_e32 v6, vcc, vcc_lo, v102
	s_nop 1
	v_addc_co_u32_e32 v7, vcc, -1, v103, vcc
	global_load_dwordx4 v[64:67], v[0:1], off offset:-192
	global_load_dwordx4 v[32:35], v[0:1], off offset:-128
	global_load_dwordx4 v[68:71], v[4:5], off offset:-192
	global_load_dwordx4 v[36:39], v[4:5], off offset:-128
	global_load_dwordx4 v[72:75], v[6:7], off offset:-192
	global_load_dwordx4 v[44:47], v[6:7], off offset:-128
	global_load_dwordx4 v[40:43], v[6:7], off offset:-64
	global_load_dwordx4 v[52:55], v[102:103], off offset:-128
	global_load_dwordx4 v[48:51], v[102:103], off offset:-64
	global_load_dwordx4 v[56:59], v[0:1], off offset:-64
	global_load_dwordx4 v[16:19], v[4:5], off offset:-4096
	global_load_dwordx4 v[60:63], v[4:5], off offset:-64
	global_load_dwordx4 v[20:23], v[4:5], off
	global_load_dwordx4 v[76:79], v[102:103], off offset:-192
	global_load_dwordx4 v[24:27], v[102:103], off offset:-4096
	global_load_dwordx4 v[28:31], v[102:103], off
	v_mad_u64_u32 v[0:1], vcc, v114, s95, v[2:3]
	v_mad_i32_i24 v1, s53, v183, v1
	v_lshl_add_u64 v[0:1], v[0:1], 0, s[74:75]
	v_lshl_add_u64 v[0:1], v[94:95], 1, v[0:1]
	s_mov_b64 vcc, 0x2800
	v_lshl_add_u64 v[2:3], v[0:1], 0, vcc
	v_add_co_u32_e32 v0, vcc, s93, v0
	s_nop 1
	v_addc_co_u32_e32 v1, vcc, 0, v1, vcc
	s_lshl_b32 vcc_lo, s67, 2
	s_mov_b32 vcc_hi, s75
	v_lshl_add_u64 v[212:213], v[100:101], 0, vcc
	v_add_co_u32_e32 v244, vcc, s52, v202
	global_load_dwordx4 v[12:15], v[212:213], off
	global_load_dwordx4 v[8:11], v[212:213], off offset:64
	global_load_dwordx2 v[112:113], v[0:1], off offset:2048
	global_load_dwordx2 v[110:111], v[2:3], off offset:32
	global_load_dwordx2 v[108:109], v[2:3], off offset:64
	global_load_dwordx2 v[106:107], v[2:3], off offset:96
	global_load_dwordx4 v[4:7], v[212:213], off offset:128
	s_nop 0
	global_load_dwordx4 v[0:3], v[212:213], off offset:192
	v_addc_co_u32_e32 v245, vcc, 0, v203, vcc
	global_load_ushort v235, v[204:205], off
	global_load_ushort v229, v[206:207], off
	global_load_ushort v223, v[208:209], off
	global_load_ushort v217, v[210:211], off
	global_load_ushort v249, v[210:211], off offset:2048
	global_load_ushort v250, v[208:209], off offset:2048
	global_load_ushort v251, v[206:207], off offset:2048
	global_load_ushort v247, v[204:205], off offset:2048
	global_load_ushort v212, v[214:215], off
	s_nop 0
	global_load_ushort v210, v[218:219], off
	global_load_ushort v209, v[224:225], off
	global_load_ushort v208, v[220:221], off
	s_nop 0
	global_load_ushort v221, v[220:221], off offset:2048
	s_nop 0
	global_load_ushort v222, v[224:225], off offset:2048
	s_nop 0
	global_load_ushort v224, v[218:219], off offset:2048
	global_load_ushort v225, v[214:215], off offset:2048
	global_load_ushort v207, v[226:227], off
	global_load_ushort v206, v[230:231], off
	global_load_ushort v205, v[232:233], off
	global_load_ushort v204, v[236:237], off
	global_load_ushort v216, v[236:237], off offset:2048
	global_load_ushort v218, v[232:233], off offset:2048
	global_load_ushort v219, v[230:231], off offset:2048
	global_load_ushort v220, v[226:227], off offset:2048
	global_load_ushort v203, v[238:239], off
	global_load_ushort v202, v[240:241], off
	global_load_ushort v90, v[242:243], off
	global_load_ushort v211, v[242:243], off offset:2048
	global_load_ushort v214, v[240:241], off offset:2048
	global_load_ushort v215, v[238:239], off offset:2048
	global_load_ushort v226, v[244:245], off offset:2048
	s_nop 0
	global_load_ushort v244, v[244:245], off
	s_waitcnt vmcnt(58)
; __device__ __forceinline__ float bf2f(bf16_t b) { return __uint_as_float(((unsigned)b) << 16); }
; __device__ __forceinline__ float sigmoidf_(float x) { return __builtin_amdgcn_rcpf(1.0f + __expf(-x)); }
; __global__ void __launch_bounds__(512, 2) mega(Params p, int ph_lo, int ph_hi) {
;     ...
;                 float lb; { const float mxl = fmaxf(l0, fmaxf(l1, l2)); const float e0 = __expf(l0 - mxl), e1 = __expf(l1 - mxl), e2 = __expf(l2 - mxl); lb = e0 / (e0 + e1 + e2); }
;                 float lf[16], kk[16]; float tot = 0.f;
; #pragma unroll
;                 for (int i = 0; i < 16; ++i) { const float fz = bf2f(fzr[i]); const float sg = sigmoidf_(fz); lf[i] = __logf(lb + (1.0f - lb) * sg); kk[i] = (1.0f - lb) * __builtin_amdgcn_rcpf(1.0f + __expf(fz)); tot += lf[i]; }
	v_max3_f32 v105, v228, v234, v246
	v_sub_f32_e32 v213, v228, v105
	v_sub_f32_e32 v227, v234, v105
	v_mul_f32_e32 v213, 0x3fb8aa3b, v213
	v_mul_f32_e32 v227, 0x3fb8aa3b, v227
	v_sub_f32_e32 v105, v246, v105
	v_exp_f32_e32 v213, v213
	v_exp_f32_e32 v227, v227
	v_mul_f32_e32 v105, 0x3fb8aa3b, v105
	v_exp_f32_e32 v105, v105
	s_waitcnt vmcnt(1)
	v_lshlrev_b32_e32 v226, 16, v226
	v_add_f32_e32 v227, v213, v227
	v_lshlrev_b32_e32 v246, 16, v247
	v_add_f32_e32 v105, v105, v227
	v_div_scale_f32 v227, s[52:53], v105, v105, v213
	v_rcp_f32_e32 v228, v227
	v_lshlrev_b32_e32 v242, 16, v251
	v_lshlrev_b32_e32 v240, 16, v250
	v_lshlrev_b32_e32 v238, 16, v249
	v_fma_f32 v230, -v227, v228, 1.0
	v_fmac_f32_e32 v228, v230, v228
	v_div_scale_f32 v230, vcc, v213, v105, v213
	v_mul_f32_e32 v231, v230, v228
	v_fma_f32 v232, -v227, v231, v230
	v_fmac_f32_e32 v231, v232, v228
	v_fma_f32 v227, -v227, v231, v230
	v_div_fmas_f32 v227, v227, v228, v231
	v_div_fixup_f32 v213, v227, v105, v213
	v_mul_f32_e32 v227, 0xbfb8aa3b, v226
	v_exp_f32_e32 v227, v227
	v_sub_f32_e32 v105, 1.0, v213
	v_lshlrev_b32_e32 v236, 16, v225
	v_mul_f32_e32 v225, 0xbfb8aa3b, v236
	v_add_f32_e32 v227, 1.0, v227
	v_rcp_f32_e32 v227, v227
	v_exp_f32_e32 v225, v225
	v_mul_f32_e32 v226, 0x3fb8aa3b, v226
	v_exp_f32_e32 v226, v226
	v_fma_f32 v227, v105, v227, v213
	v_cmp_gt_f32_e32 vcc, s97, v227
	v_add_f32_e32 v225, 1.0, v225
	v_rcp_f32_e32 v225, v225
	v_cndmask_b32_e64 v228, 0, 32, vcc
	v_ldexp_f32 v227, v227, v228
	v_log_f32_e32 v227, v227
	v_fma_f32 v225, v105, v225, v213
	v_lshlrev_b32_e32 v233, 16, v224
	v_mul_f32_e32 v224, 0xbfb8aa3b, v233
	v_mul_f32_e32 v228, 0x3f317217, v227
	v_fma_f32 v228, v227, s39, -v228
	v_fmac_f32_e32 v228, 0x3377d1cf, v227
	v_fmac_f32_e32 v228, 0x3f317217, v227
	v_cmp_lt_f32_e64 s[52:53], |v227|, s33
	v_exp_f32_e32 v224, v224
	v_add_f32_e32 v226, 1.0, v226
	v_cndmask_b32_e64 v227, v227, v228, s[52:53]
	v_cndmask_b32_e32 v228, 0, v184, vcc
	v_sub_f32_e32 v248, v227, v228
	v_mul_f32_e32 v227, 0xbfb8aa3b, v246
	v_exp_f32_e32 v227, v227
	v_rcp_f32_e32 v226, v226
	v_add_f32_e32 v224, 1.0, v224
	v_rcp_f32_e32 v224, v224
	v_add_f32_e32 v227, 1.0, v227
	v_rcp_f32_e32 v227, v227
	v_mul_f32_e32 v243, v105, v226
	v_add_f32_e32 v226, 0, v248
	v_fma_f32 v224, v105, v224, v213
	v_fma_f32 v227, v105, v227, v213
	v_cmp_gt_f32_e32 vcc, s97, v227
	v_lshlrev_b32_e32 v231, 16, v222
	v_mul_f32_e32 v222, 0xbfb8aa3b, v231
	v_cndmask_b32_e64 v228, 0, 32, vcc
	v_ldexp_f32 v227, v227, v228
	v_log_f32_e32 v227, v227
	v_exp_f32_e32 v222, v222
	v_lshlrev_b32_e32 v214, 16, v214
	v_lshlrev_b32_e32 v211, 16, v211
	v_mul_f32_e32 v228, 0x3f317217, v227
	v_fma_f32 v228, v227, s39, -v228
	v_fmac_f32_e32 v228, 0x3377d1cf, v227
	v_fmac_f32_e32 v228, 0x3f317217, v227
	v_cmp_lt_f32_e64 s[52:53], |v227|, s33
	v_add_f32_e32 v222, 1.0, v222
	v_rcp_f32_e32 v222, v222
	v_cndmask_b32_e64 v227, v227, v228, s[52:53]
	v_cndmask_b32_e32 v228, 0, v184, vcc
	v_sub_f32_e32 v247, v227, v228
	v_mul_f32_e32 v227, 0xbfb8aa3b, v242
	v_exp_f32_e32 v227, v227
	v_add_f32_e32 v226, v226, v247
	v_fma_f32 v222, v105, v222, v213
	v_add_f32_e32 v227, 1.0, v227
	v_rcp_f32_e32 v227, v227
	s_barrier
	v_fma_f32 v227, v105, v227, v213
	v_cmp_gt_f32_e32 vcc, s97, v227
	s_nop 1
	v_cndmask_b32_e64 v228, 0, 32, vcc
	v_ldexp_f32 v227, v227, v228
	v_log_f32_e32 v227, v227
	s_nop 0
	v_mul_f32_e32 v228, 0x3f317217, v227
	v_fma_f32 v228, v227, s39, -v228
	v_fmac_f32_e32 v228, 0x3377d1cf, v227
	v_fmac_f32_e32 v228, 0x3f317217, v227
	v_cmp_lt_f32_e64 s[52:53], |v227|, s33
	s_nop 1
	v_cndmask_b32_e64 v227, v227, v228, s[52:53]
	v_cndmask_b32_e32 v228, 0, v184, vcc
	v_sub_f32_e32 v245, v227, v228
	v_mul_f32_e32 v227, 0xbfb8aa3b, v240
	v_exp_f32_e32 v227, v227
	v_add_f32_e32 v226, v226, v245
	v_add_f32_e32 v227, 1.0, v227
	v_rcp_f32_e32 v227, v227
	s_nop 0
	v_fma_f32 v227, v105, v227, v213
	v_cmp_gt_f32_e32 vcc, s97, v227
	s_nop 1
	v_cndmask_b32_e64 v228, 0, 32, vcc
	v_ldexp_f32 v227, v227, v228
	v_log_f32_e32 v227, v227
	s_nop 0
	v_mul_f32_e32 v228, 0x3f317217, v227
	v_fma_f32 v228, v227, s39, -v228
	v_fmac_f32_e32 v228, 0x3377d1cf, v227
	v_fmac_f32_e32 v228, 0x3f317217, v227
	v_cmp_lt_f32_e64 s[52:53], |v227|, s33
	s_nop 1
	v_cndmask_b32_e64 v227, v227, v228, s[52:53]
	v_cndmask_b32_e32 v228, 0, v184, vcc
	v_sub_f32_e32 v241, v227, v228
	v_mul_f32_e32 v227, 0xbfb8aa3b, v238
	v_exp_f32_e32 v227, v227
	v_add_f32_e32 v226, v226, v241
	v_add_f32_e32 v227, 1.0, v227
	v_rcp_f32_e32 v227, v227
	s_nop 0
	v_fma_f32 v227, v105, v227, v213
	v_cmp_gt_f32_e32 vcc, s97, v227
	s_nop 1
	v_cndmask_b32_e64 v228, 0, 32, vcc
	v_ldexp_f32 v227, v227, v228
	v_log_f32_e32 v227, v227
	s_nop 0
	v_mul_f32_e32 v228, 0x3f317217, v227
	v_fma_f32 v228, v227, s39, -v228
	v_fmac_f32_e32 v228, 0x3377d1cf, v227
	v_fmac_f32_e32 v228, 0x3f317217, v227
	v_cmp_lt_f32_e64 s[52:53], |v227|, s33
	s_nop 1
	v_cndmask_b32_e64 v227, v227, v228, s[52:53]
	v_cndmask_b32_e32 v228, 0, v184, vcc
	v_cmp_gt_f32_e32 vcc, s97, v225
	v_sub_f32_e32 v239, v227, v228
	v_add_f32_e32 v226, v226, v239
	v_cndmask_b32_e64 v227, 0, 32, vcc
	v_ldexp_f32 v225, v225, v227
	v_log_f32_e32 v225, v225
	v_lshlrev_b32_e32 v228, 16, v221
	v_mul_f32_e32 v221, 0xbfb8aa3b, v228
	v_exp_f32_e32 v221, v221
	v_mul_f32_e32 v227, 0x3f317217, v225
	v_fma_f32 v227, v225, s39, -v227
	v_fmac_f32_e32 v227, 0x3377d1cf, v225
	v_fmac_f32_e32 v227, 0x3f317217, v225
	v_cmp_lt_f32_e64 s[52:53], |v225|, s33
	v_add_f32_e32 v221, 1.0, v221
	v_rcp_f32_e32 v221, v221
	v_cndmask_b32_e64 v225, v225, v227, s[52:53]
	v_cndmask_b32_e32 v227, 0, v184, vcc
	v_sub_f32_e32 v237, v225, v227
	v_cmp_gt_f32_e32 vcc, s97, v224
	v_add_f32_e32 v225, v226, v237
; #define LAS __attribute__((address_space(3)))
; __device__ __forceinline__ float bf2f(bf16_t b) { return __uint_as_float(((unsigned)b) << 16); }
; __device__ __forceinline__ float sigmoidf_(float x) { return __builtin_amdgcn_rcpf(1.0f + __expf(-x)); }
; __global__ void __launch_bounds__(512, 2) mega(Params p, int ph_lo, int ph_hi) {
;     ...
;                 for (int i = 0; i < 16; ++i) { const float fz = bf2f(fzr[i]); const float sg = sigmoidf_(fz); lf[i] = __logf(lb + (1.0f - lb) * sg); kk[i] = (1.0f - lb) * __builtin_amdgcn_rcpf(1.0f + __expf(fz)); tot += lf[i]; }
;                 __syncthreads();
;                 EX[I * 128 + k] = tot; EX[512 + I * 128 + k] = lf[0];
; #pragma unroll
;                 for (int i = 0; i < 2; ++i) { const int idx = tid + 512 * i, r = idx >> 4, ch = idx & 15; *(LAS u32x4*)(VS + (r * HP + 8 * ch) * 2) = vst[i]; }
;                 __syncthreads();
	v_fma_f32 v221, v105, v221, v213
	v_cndmask_b32_e64 v226, 0, 32, vcc
	v_ldexp_f32 v224, v224, v226
	v_log_f32_e32 v224, v224
	s_nop 0
	v_mul_f32_e32 v226, 0x3f317217, v224
	v_fma_f32 v226, v224, s39, -v226
	v_fmac_f32_e32 v226, 0x3377d1cf, v224
	v_fmac_f32_e32 v226, 0x3f317217, v224
	v_cmp_lt_f32_e64 s[52:53], |v224|, s33
	s_nop 1
	v_cndmask_b32_e64 v224, v224, v226, s[52:53]
	v_cndmask_b32_e32 v226, 0, v184, vcc
	v_sub_f32_e32 v234, v224, v226
	v_cmp_gt_f32_e32 vcc, s97, v222
	v_add_f32_e32 v224, v225, v234
	v_lshlrev_b32_e32 v226, 16, v220
	v_cndmask_b32_e64 v225, 0, 32, vcc
	v_ldexp_f32 v222, v222, v225
	v_log_f32_e32 v222, v222
	v_mul_f32_e32 v220, 0xbfb8aa3b, v226
	v_exp_f32_e32 v220, v220
	v_mul_f32_e32 v225, 0x3f317217, v222
	v_fma_f32 v225, v222, s39, -v225
	v_fmac_f32_e32 v225, 0x3377d1cf, v222
	v_fmac_f32_e32 v225, 0x3f317217, v222
	v_cmp_lt_f32_e64 s[52:53], |v222|, s33
	v_add_f32_e32 v220, 1.0, v220
	v_rcp_f32_e32 v220, v220
	v_cndmask_b32_e64 v222, v222, v225, s[52:53]
	v_cndmask_b32_e32 v225, 0, v184, vcc
	v_sub_f32_e32 v232, v222, v225
	v_cmp_gt_f32_e32 vcc, s97, v221
	v_add_f32_e32 v222, v224, v232
	v_fma_f32 v220, v105, v220, v213
	v_cndmask_b32_e64 v224, 0, 32, vcc
	v_ldexp_f32 v221, v221, v224
	v_log_f32_e32 v221, v221
	s_nop 0
	v_mul_f32_e32 v224, 0x3f317217, v221
	v_fma_f32 v224, v221, s39, -v224
	v_fmac_f32_e32 v224, 0x3377d1cf, v221
	v_fmac_f32_e32 v224, 0x3f317217, v221
	v_cmp_lt_f32_e64 s[52:53], |v221|, s33
	s_nop 1
	v_cndmask_b32_e64 v221, v221, v224, s[52:53]
	v_cndmask_b32_e32 v224, 0, v184, vcc
	v_sub_f32_e32 v230, v221, v224
	v_cmp_gt_f32_e32 vcc, s97, v220
	v_lshlrev_b32_e32 v224, 16, v219
	v_add_f32_e32 v221, v222, v230
	v_cndmask_b32_e64 v222, 0, 32, vcc
	v_mul_f32_e32 v219, 0xbfb8aa3b, v224
	v_ldexp_f32 v220, v220, v222
	v_exp_f32_e32 v219, v219
	v_log_f32_e32 v220, v220
	v_add_f32_e32 v219, 1.0, v219
	v_mul_f32_e32 v222, 0x3f317217, v220
	v_rcp_f32_e32 v219, v219
	v_fma_f32 v222, v220, s39, -v222
	v_fmac_f32_e32 v222, 0x3377d1cf, v220
	v_fmac_f32_e32 v222, 0x3f317217, v220
	v_cmp_lt_f32_e64 s[52:53], |v220|, s33
	v_fma_f32 v219, v105, v219, v213
	s_nop 0
	v_cndmask_b32_e64 v220, v220, v222, s[52:53]
	v_cndmask_b32_e32 v222, 0, v184, vcc
	v_sub_f32_e32 v227, v220, v222
	v_cmp_gt_f32_e32 vcc, s97, v219
	v_add_f32_e32 v220, v221, v227
	s_nop 0
	v_cndmask_b32_e64 v221, 0, 32, vcc
	v_ldexp_f32 v219, v219, v221
	v_log_f32_e32 v219, v219
	s_nop 0
	v_mul_f32_e32 v221, 0x3f317217, v219
	v_fma_f32 v221, v219, s39, -v221
	v_fmac_f32_e32 v221, 0x3377d1cf, v219
	v_fmac_f32_e32 v221, 0x3f317217, v219
	v_cmp_lt_f32_e64 s[52:53], |v219|, s33
	s_nop 1
	v_cndmask_b32_e64 v219, v219, v221, s[52:53]
	v_cndmask_b32_e32 v221, 0, v184, vcc
	v_sub_f32_e32 v225, v219, v221
	v_lshlrev_b32_e32 v221, 16, v218
	v_mul_f32_e32 v218, 0xbfb8aa3b, v221
	v_exp_f32_e32 v218, v218
	v_add_f32_e32 v219, v220, v225
	v_add_f32_e32 v218, 1.0, v218
	v_rcp_f32_e32 v218, v218
	s_nop 0
	v_fma_f32 v218, v105, v218, v213
	v_cmp_gt_f32_e32 vcc, s97, v218
	s_nop 1
	v_cndmask_b32_e64 v220, 0, 32, vcc
	v_ldexp_f32 v218, v218, v220
	v_log_f32_e32 v218, v218
	s_nop 0
	v_mul_f32_e32 v220, 0x3f317217, v218
	v_fma_f32 v220, v218, s39, -v220
	v_fmac_f32_e32 v220, 0x3377d1cf, v218
	v_fmac_f32_e32 v220, 0x3f317217, v218
	v_cmp_lt_f32_e64 s[52:53], |v218|, s33
	s_nop 1
	v_cndmask_b32_e64 v218, v218, v220, s[52:53]
	v_cndmask_b32_e32 v220, 0, v184, vcc
	v_sub_f32_e32 v222, v218, v220
	v_add_f32_e32 v218, v219, v222
	v_lshlrev_b32_e32 v219, 16, v216
	v_mul_f32_e32 v216, 0xbfb8aa3b, v219
	v_exp_f32_e32 v216, v216
	s_nop 0
	v_add_f32_e32 v216, 1.0, v216
	v_rcp_f32_e32 v216, v216
	s_nop 0
	v_fma_f32 v216, v105, v216, v213
	v_cmp_gt_f32_e32 vcc, s97, v216
	s_nop 1
	v_cndmask_b32_e64 v220, 0, 32, vcc
	v_ldexp_f32 v216, v216, v220
	v_log_f32_e32 v216, v216
	s_nop 0
	v_mul_f32_e32 v220, 0x3f317217, v216
	v_fma_f32 v220, v216, s39, -v220
	v_fmac_f32_e32 v220, 0x3377d1cf, v216
	v_fmac_f32_e32 v220, 0x3f317217, v216
	v_cmp_lt_f32_e64 s[52:53], |v216|, s33
	s_nop 1
	v_cndmask_b32_e64 v216, v216, v220, s[52:53]
	v_cndmask_b32_e32 v220, 0, v184, vcc
	v_sub_f32_e32 v220, v216, v220
	v_lshlrev_b32_e32 v216, 16, v215
	v_mul_f32_e32 v215, 0xbfb8aa3b, v216
	v_exp_f32_e32 v215, v215
	v_add_f32_e32 v249, v218, v220
	v_add_f32_e32 v215, 1.0, v215
	v_rcp_f32_e32 v215, v215
	s_nop 0
	v_fma_f32 v215, v105, v215, v213
	v_cmp_gt_f32_e32 vcc, s97, v215
	s_nop 1
	v_cndmask_b32_e64 v218, 0, 32, vcc
	v_ldexp_f32 v215, v215, v218
	v_log_f32_e32 v215, v215
	s_nop 0
	v_mul_f32_e32 v218, 0x3f317217, v215
	v_fma_f32 v218, v215, s39, -v218
	v_fmac_f32_e32 v218, 0x3377d1cf, v215
	v_fmac_f32_e32 v218, 0x3f317217, v215
	v_cmp_lt_f32_e64 s[52:53], |v215|, s33
	s_nop 1
	v_cndmask_b32_e64 v215, v215, v218, s[52:53]
	v_cndmask_b32_e32 v218, 0, v184, vcc
	v_sub_f32_e32 v218, v215, v218
	v_mul_f32_e32 v215, 0xbfb8aa3b, v214
	v_exp_f32_e32 v215, v215
	v_add_f32_e32 v249, v249, v218
	v_add_f32_e32 v215, 1.0, v215
	v_rcp_f32_e32 v215, v215
	s_nop 0
	v_fma_f32 v215, v105, v215, v213
	v_cmp_gt_f32_e32 vcc, s97, v215
	s_nop 1
	v_cndmask_b32_e64 v250, 0, 32, vcc
	v_ldexp_f32 v215, v215, v250
	v_log_f32_e32 v215, v215
	s_nop 0
	v_mul_f32_e32 v250, 0x3f317217, v215
	v_fma_f32 v250, v215, s39, -v250
	v_fmac_f32_e32 v250, 0x3377d1cf, v215
	v_fmac_f32_e32 v250, 0x3f317217, v215
	v_cmp_lt_f32_e64 s[52:53], |v215|, s33
	s_nop 1
	v_cndmask_b32_e64 v215, v215, v250, s[52:53]
	v_cndmask_b32_e32 v250, 0, v184, vcc
	v_sub_f32_e32 v215, v215, v250
	v_mul_f32_e32 v250, 0xbfb8aa3b, v211
	v_exp_f32_e32 v250, v250
	v_add_f32_e32 v249, v249, v215
	v_add_f32_e32 v250, 1.0, v250
	v_rcp_f32_e32 v250, v250
	s_nop 0
	v_fmac_f32_e32 v213, v105, v250
	v_cmp_gt_f32_e32 vcc, s97, v213
	s_nop 1
	v_cndmask_b32_e64 v250, 0, 32, vcc
	v_ldexp_f32 v213, v213, v250
	v_log_f32_e32 v213, v213
	s_nop 0
	v_mul_f32_e32 v250, 0x3f317217, v213
	v_fma_f32 v250, v213, s39, -v250
	v_fmac_f32_e32 v250, 0x3377d1cf, v213
	v_fmac_f32_e32 v250, 0x3f317217, v213
	v_cmp_lt_f32_e64 s[52:53], |v213|, s33
	s_nop 1
	v_cndmask_b32_e64 v213, v213, v250, s[52:53]
	v_cndmask_b32_e32 v250, 0, v184, vcc
	v_sub_f32_e32 v213, v213, v250
	v_add_f32_e32 v249, v249, v213
	ds_write_b32 v116, v249
	ds_write_b32 v118, v248 offset:2048
	ds_write_b128 v125, v[80:83] offset:34816
	ds_write_b128 v126, v[84:87] offset:34816
	s_waitcnt lgkmcnt(0)
	s_barrier
; #define LAS __attribute__((address_space(3)))
; __device__ __forceinline__ float bf2f(bf16_t b) { return __uint_as_float(((unsigned)b) << 16); }
; __device__ __forceinline__ float siluf_(float x) { return x * __builtin_amdgcn_rcpf(1.0f + __expf(-x)); }
; __global__ void __launch_bounds__(512, 2) mega(Params p, int ph_lo, int ph_hi) {
;     ...
;                 float bref[4]; float prefix = 0.f;
;                 { float run = 0.f;
; #pragma unroll
;                   for (int ii = 0; ii < 4; ++ii) { bref[ii] = run + EX[512 + ii * 128 + k]; if (ii == I) prefix = run; run += EX[ii * 128 + k]; } }
;                 float brefI = bref[0];
; #pragma unroll
;                 for (int ii = 1; ii < 4; ++ii) if (ii == I) brefI = bref[ii];
;                 float bc = prefix;
; #pragma unroll
;                 for (int i = 0; i < 16; ++i) {
;                     bc += lf[i];
;                     const int t = 16 * I + i;
;                     const float qs = siluf_(bf2f(qr[i]));
;                     *(LAS bf16_t*)(QT + (t * HP + k) * 2) = (bf16_t)(pk2(qs * __expf(bc), 0.f) & 0xffffu);
;                     *(LAS bf16_t*)(AI + (t * HP + k) * 2) = (bf16_t)(pk2(qs * __expf(bc - brefI), 0.f) & 0xffffu);
	ds_read2st64_b32 v[84:85], v117 offset0:4 offset1:8
	ds_read2st64_b32 v[86:87], v117 offset1:2
	ds_read2st64_b32 v[250:251], v117 offset0:10 offset1:12
	ds_read_b32 v83, v117 offset:3584
	s_waitcnt lgkmcnt(3)
	v_add_f32_e32 v82, 0, v85
	s_waitcnt lgkmcnt(2)
	v_add_f32_e32 v85, 0, v86
	s_waitcnt lgkmcnt(1)
	v_add_f32_e32 v81, v85, v250
	v_add_f32_e32 v86, v85, v87
	v_cndmask_b32_e64 v85, 0, v85, s[4:5]
	v_add_f32_e32 v80, v86, v251
	v_add_f32_e32 v87, v86, v84
	v_cndmask_b32_e64 v85, v85, v86, s[6:7]
	s_waitcnt vmcnt(0)
	s_add_i32 s98, s66, s94
	s_cmpk_ge_i32 s98, 0x800
	s_cbranch_scc1 .Lh3_nopf
	s_and_b32 s99, s98, 0x7f
	s_lshr_b32 s100, s98, 7
	s_and_b32 s101, s100, 7
	s_lshr_b32 s100, s100, 3
	s_lshl_b32 s100, s100, 13
	s_lshl_b32 s99, s99, 6
	s_add_i32 s100, s100, s99
	s_mul_i32 s100, s100, 0x3000
	s_lshl_b32 s101, s101, 8
	s_add_u32 s100, s100, s101
	s_add_u32 s100, s100, 0xa800000
	s_add_u32 s100, s90, s100
	s_addc_u32 s101, s91, 0
	global_load_dword v255, v254, s[100:101]
	s_lshl_b32 s98, s98, 15
	s_add_u32 s98, s88, s98
	s_addc_u32 s99, s89, 0
	global_load_dword v255, v252, s[98:99]
.Lh3_nopf:
	v_lshlrev_b32_e32 v86, 16, v244
	s_waitcnt lgkmcnt(0)
	v_add_f32_e32 v83, v87, v83
	v_cndmask_b32_e64 v85, v85, v87, s[8:9]
	v_mul_f32_e32 v87, 0xbfb8aa3b, v86
	v_exp_f32_e32 v87, v87
	v_add_f32_e32 v85, v85, v248
	v_cndmask_b32_e64 v84, v82, v81, s[4:5]
	v_cndmask_b32_e64 v84, v84, v80, s[6:7]
	v_add_f32_e32 v87, 1.0, v87
	v_rcp_f32_e32 v87, v87
	v_cndmask_b32_e64 v84, v84, v83, s[8:9]
	v_mul_f32_e32 v87, v87, v86
	v_mul_f32_e32 v86, 0x3fb8aa3b, v85
	v_exp_f32_e32 v86, v86
	s_nop 0
	v_mul_f32_e32 v86, v86, v87
	v_cvt_pk_bf16_f32 v244, v86, s0
	v_add_u32_e32 v86, 0, v121
	ds_write_b16 v86, v244
	v_sub_f32_e32 v244, v85, v84
	v_mul_f32_e32 v244, 0x3fb8aa3b, v244
	v_exp_f32_e32 v244, v244
	s_nop 0
	v_mul_f32_e32 v87, v244, v87
	v_cvt_pk_bf16_f32 v87, v87, s0
	ds_write_b16 v86, v87 offset:17408
	s_and_saveexec_b64 s[52:53], s[10:11]
	s_cbranch_execnz .LBB0_503
	s_or_b64 exec, exec, s[52:53]
	s_and_saveexec_b64 s[52:53], s[12:13]
	s_cbranch_execnz .LBB0_504

; #define PG8_STAGE(bufoff, gbase, voff) do { _Pragma("unroll") for (int _i = 0; _i < 2; ++_i) \
;         __builtin_amdgcn_global_load_lds((const unsigned*)((const char*)(gbase) + (voff)[_i]), (LAS unsigned*)(lds + (bufoff) + ldsw + _i * 8192), 16, 0, 0); } while (0)
; #define PG8_LDA(dst, b, h) do { _Pragma("unroll") for (int m = 0; m < 4; ++m) _Pragma("unroll") for (int k = 0; k < 2; ++k) dst[m][k] = *(const LAS bf16x8*)(lds + PG8_SA(b, h) + aoff + m * 2048 + k * 1024); } while (0)
; #define PG8_LDB(dst, b, h) do { _Pragma("unroll") for (int n = 0; n < 2; ++n) _Pragma("unroll") for (int k = 0; k < 2; ++k) dst[n][k] = *(const LAS bf16x8*)(lds + PG8_SB(b, h) + boff + n * 2048 + k * 1024); } while (0)
; #define PG8_MMA(ai, bj, At, Bt) do { __builtin_amdgcn_s_setprio(1); _Pragma("unroll") for (int m = 0; m < 4; ++m) _Pragma("unroll") for (int n = 0; n < 2; ++n) _Pragma("unroll") for (int k = 0; k < 2; ++k) \
;         acc[ai][bj][m][n] = __builtin_amdgcn_mfma_f32_16x16x32_bf16(Bt[n][k], At[m][k], acc[ai][bj][m][n], 0, 0, 0); __builtin_amdgcn_s_setprio(0); } while (0)
; #define PG8_WAIT_L(n) asm volatile("s_waitcnt lgkmcnt(" #n ")" ::: "memory")
; #define PG8_BAR __builtin_amdgcn_s_barrier()
; #define PG8_SCHED __builtin_amdgcn_sched_barrier(0)
; template <class Epi>
; __device__ __forceinline__ void gemm_phase(LAS unsigned char* lds, const Gemm g, const Order& S, const Epi& E, const int tid) {
;     ...
;             PG8_LDB(B0, 0, 0); PG8_SCHED; PG8_LDA(At, 0, 0); PG8_STAGE(PG8_SA(1, 1), a1 + hstepA, voffA);
;             PG8_WAIT_L(8); PG8_BAR; PG8_WAIT_L(0); PG8_MMA(0, 0, At, B0); PG8_BAR; PG8_SCHED;
;             PG8_LDB(B1, 0, 1); PG8_STAGE(PG8_SB(0, 0), b2, voffB);
;             PG8_BAR; PG8_WAIT_L(0); PG8_MMA(0, 1, At, B1); PG8_BAR;
;             PG8_LDA(At, 0, 1); PG8_STAGE(PG8_SA(0, 0), a2, voffA);
;             PG8_BAR; PG8_WAIT_L(0); PG8_MMA(1, 0, At, B0); PG8_BAR; PG8_SCHED;
.LBB0_747:
	ds_read_b128 v[142:145], v150
	ds_read_b128 v[154:157], v150 offset:1024
	ds_read_b128 v[158:161], v150 offset:2048
	ds_read_b128 v[162:165], v150 offset:3072
	s_add_u32 s20, s18, 0xfff80080
	s_addc_u32 s21, s19, -1
	s_cmp_eq_u32 s51, 28
	s_cselect_b32 s27, s5, s21
	s_cselect_b32 s26, s11, s20
	s_cselect_b32 s21, s13, s50
	s_cselect_b32 s20, s48, s49
	v_lshl_add_u64 v[198:199], s[18:19], 0, v[134:135]
	s_add_i32 m0, s31, 0xc000
	ds_read_b128 v[166:169], v151
	ds_read_b128 v[170:173], v151 offset:1024
	ds_read_b128 v[174:177], v151 offset:2048
	ds_read_b128 v[178:181], v151 offset:3072
	ds_read_b128 v[182:185], v151 offset:4096
	ds_read_b128 v[186:189], v151 offset:5120
	ds_read_b128 v[190:193], v151 offset:6144
	ds_read_b128 v[194:197], v151 offset:7168
	global_load_lds_dwordx4 v[198:199], off
	v_lshl_add_u64 v[198:199], s[18:19], 0, v[136:137]
	s_add_i32 m0, s31, 0xe000
	s_nop 0
	global_load_lds_dwordx4 v[198:199], off
	s_waitcnt lgkmcnt(8)
	s_barrier
	s_waitcnt lgkmcnt(0)
	s_setprio 1
	s_waitcnt lgkmcnt(0)
	v_mfma_f32_16x16x32_bf16 v[124:127], v[142:145], v[166:169], v[124:127]
	v_mfma_f32_16x16x32_bf16 v[120:123], v[158:161], v[166:169], v[120:123]
	v_mfma_f32_16x16x32_bf16 v[108:111], v[142:145], v[174:177], v[108:111]
	v_mfma_f32_16x16x32_bf16 v[104:107], v[158:161], v[174:177], v[104:107]
	v_mfma_f32_16x16x32_bf16 v[92:95], v[142:145], v[182:185], v[92:95]
	v_mfma_f32_16x16x32_bf16 v[88:91], v[158:161], v[182:185], v[88:91]
	v_mfma_f32_16x16x32_bf16 v[76:79], v[142:145], v[190:193], v[76:79]
	v_mfma_f32_16x16x32_bf16 v[72:75], v[158:161], v[190:193], v[72:75]
	v_mfma_f32_16x16x32_bf16 v[124:127], v[154:157], v[170:173], v[124:127]
	v_mfma_f32_16x16x32_bf16 v[120:123], v[162:165], v[170:173], v[120:123]
	v_mfma_f32_16x16x32_bf16 v[108:111], v[154:157], v[178:181], v[108:111]
	v_mfma_f32_16x16x32_bf16 v[104:107], v[162:165], v[178:181], v[104:107]
	v_mfma_f32_16x16x32_bf16 v[92:95], v[154:157], v[186:189], v[92:95]
	v_mfma_f32_16x16x32_bf16 v[88:91], v[162:165], v[186:189], v[88:91]
	v_mfma_f32_16x16x32_bf16 v[76:79], v[154:157], v[194:197], v[76:79]
	v_mfma_f32_16x16x32_bf16 v[72:75], v[162:165], v[194:197], v[72:75]
	s_setprio 0
	s_barrier
	s_add_i32 s52, s41, s29
	v_lshl_add_u64 v[214:215], s[20:21], 0, v[130:131]
	s_mov_b32 m0, s52
	ds_read_b128 v[198:201], v152
	ds_read_b128 v[202:205], v152 offset:1024
	ds_read_b128 v[206:209], v152 offset:2048
	ds_read_b128 v[210:213], v152 offset:3072
	global_load_lds_dwordx4 v[214:215], off
	v_lshl_add_u64 v[216:217], s[20:21], 0, v[128:129]
	s_add_i32 m0, s52, 0x2000
	s_nop 0
	global_load_lds_dwordx4 v[216:217], off
	s_barrier
	s_waitcnt lgkmcnt(0)
	s_setprio 1
	s_waitcnt lgkmcnt(0)
	v_mfma_f32_16x16x32_bf16 v[116:119], v[198:201], v[166:169], v[116:119]
	v_mfma_f32_16x16x32_bf16 v[112:115], v[206:209], v[166:169], v[112:115]
	v_mfma_f32_16x16x32_bf16 v[100:103], v[198:201], v[174:177], v[100:103]
	v_mfma_f32_16x16x32_bf16 v[96:99], v[206:209], v[174:177], v[96:99]
	v_mfma_f32_16x16x32_bf16 v[84:87], v[198:201], v[182:185], v[84:87]
	v_mfma_f32_16x16x32_bf16 v[80:83], v[206:209], v[182:185], v[80:83]
	v_mfma_f32_16x16x32_bf16 v[68:71], v[198:201], v[190:193], v[68:71]
	v_mfma_f32_16x16x32_bf16 v[64:67], v[206:209], v[190:193], v[64:67]
	v_mfma_f32_16x16x32_bf16 v[116:119], v[202:205], v[170:173], v[116:119]
	v_mfma_f32_16x16x32_bf16 v[112:115], v[210:213], v[170:173], v[112:115]
	v_mfma_f32_16x16x32_bf16 v[100:103], v[202:205], v[178:181], v[100:103]
	v_mfma_f32_16x16x32_bf16 v[96:99], v[210:213], v[178:181], v[96:99]
	v_mfma_f32_16x16x32_bf16 v[84:87], v[202:205], v[186:189], v[84:87]
	v_mfma_f32_16x16x32_bf16 v[80:83], v[210:213], v[186:189], v[80:83]
	v_mfma_f32_16x16x32_bf16 v[68:71], v[202:205], v[194:197], v[68:71]
	v_mfma_f32_16x16x32_bf16 v[64:67], v[210:213], v[194:197], v[64:67]
	s_setprio 0
	s_mov_b32 m0, s31
	v_lshl_add_u64 v[218:219], s[26:27], 0, v[130:131]
	s_barrier
	ds_read_b128 v[166:169], v151 offset:16384
	ds_read_b128 v[170:173], v151 offset:17408
	ds_read_b128 v[174:177], v151 offset:18432
	ds_read_b128 v[178:181], v151 offset:19456
	ds_read_b128 v[182:185], v151 offset:20480
	ds_read_b128 v[186:189], v151 offset:21504
	ds_read_b128 v[190:193], v151 offset:22528
	ds_read_b128 v[194:197], v151 offset:23552
	global_load_lds_dwordx4 v[218:219], off
	v_lshl_add_u64 v[220:221], s[26:27], 0, v[128:129]
	s_mov_b32 m0, s33
	s_nop 0
	global_load_lds_dwordx4 v[220:221], off
	s_barrier
	s_waitcnt lgkmcnt(0)
	s_setprio 1
	s_waitcnt lgkmcnt(0)
	v_mfma_f32_16x16x32_bf16 v[60:63], v[142:145], v[166:169], v[60:63]
	v_mfma_f32_16x16x32_bf16 v[56:59], v[158:161], v[166:169], v[56:59]
	v_mfma_f32_16x16x32_bf16 v[44:47], v[142:145], v[174:177], v[44:47]
	v_mfma_f32_16x16x32_bf16 v[40:43], v[158:161], v[174:177], v[40:43]
	v_mfma_f32_16x16x32_bf16 v[28:31], v[142:145], v[182:185], v[28:31]
	v_mfma_f32_16x16x32_bf16 v[24:27], v[158:161], v[182:185], v[24:27]
	v_mfma_f32_16x16x32_bf16 v[12:15], v[142:145], v[190:193], v[12:15]
	v_mfma_f32_16x16x32_bf16 v[8:11], v[158:161], v[190:193], v[8:11]
	v_mfma_f32_16x16x32_bf16 v[60:63], v[154:157], v[170:173], v[60:63]
	v_mfma_f32_16x16x32_bf16 v[56:59], v[162:165], v[170:173], v[56:59]
	v_mfma_f32_16x16x32_bf16 v[44:47], v[154:157], v[178:181], v[44:47]
	v_mfma_f32_16x16x32_bf16 v[40:43], v[162:165], v[178:181], v[40:43]
	v_mfma_f32_16x16x32_bf16 v[28:31], v[154:157], v[186:189], v[28:31]
	v_mfma_f32_16x16x32_bf16 v[24:27], v[162:165], v[186:189], v[24:27]
	v_mfma_f32_16x16x32_bf16 v[12:15], v[154:157], v[194:197], v[12:15]
	v_mfma_f32_16x16x32_bf16 v[8:11], v[162:165], v[194:197], v[8:11]
	s_setprio 0
	s_barrier
; #define PG8_STAGE(bufoff, gbase, voff) do { _Pragma("unroll") for (int _i = 0; _i < 2; ++_i) \
;         __builtin_amdgcn_global_load_lds((const unsigned*)((const char*)(gbase) + (voff)[_i]), (LAS unsigned*)(lds + (bufoff) + ldsw + _i * 8192), 16, 0, 0); } while (0)
; #define PG8_LDA(dst, b, h) do { _Pragma("unroll") for (int m = 0; m < 4; ++m) _Pragma("unroll") for (int k = 0; k < 2; ++k) dst[m][k] = *(const LAS bf16x8*)(lds + PG8_SA(b, h) + aoff + m * 2048 + k * 1024); } while (0)
; #define PG8_LDB(dst, b, h) do { _Pragma("unroll") for (int n = 0; n < 2; ++n) _Pragma("unroll") for (int k = 0; k < 2; ++k) dst[n][k] = *(const LAS bf16x8*)(lds + PG8_SB(b, h) + boff + n * 2048 + k * 1024); } while (0)
; #define PG8_MMA(ai, bj, At, Bt) do { __builtin_amdgcn_s_setprio(1); _Pragma("unroll") for (int m = 0; m < 4; ++m) _Pragma("unroll") for (int n = 0; n < 2; ++n) _Pragma("unroll") for (int k = 0; k < 2; ++k) \
;         acc[ai][bj][m][n] = __builtin_amdgcn_mfma_f32_16x16x32_bf16(Bt[n][k], At[m][k], acc[ai][bj][m][n], 0, 0, 0); __builtin_amdgcn_s_setprio(0); } while (0)
; #define PG8_WAIT_V(n) asm volatile("s_waitcnt vmcnt(" #n ")" ::: "memory")
; #define PG8_WAIT_L(n) asm volatile("s_waitcnt lgkmcnt(" #n ")" ::: "memory")
; #define PG8_BAR __builtin_amdgcn_s_barrier()
; #define PG8_SCHED __builtin_amdgcn_sched_barrier(0)
; template <class Epi>
; __device__ __forceinline__ void gemm_phase(LAS unsigned char* lds, const Gemm g, const Order& S, const Epi& E, const int tid) {
;     ...
;             PG8_STAGE(PG8_SB(0, 1), b2 + hstepB, voffB);
;             PG8_WAIT_V(6); PG8_BAR; PG8_MMA(1, 1, At, B1); PG8_BAR;
;             PG8_LDB(B0, 1, 0); PG8_SCHED; PG8_LDA(At, 1, 0); PG8_STAGE(PG8_SA(0, 1), a2 + hstepA, voffA);
;             PG8_WAIT_L(8); PG8_BAR; PG8_WAIT_L(0); PG8_MMA(0, 0, At, B0); PG8_BAR; PG8_SCHED;
;             PG8_LDB(B1, 1, 1); PG8_STAGE(PG8_SB(1, 0), b3, voffB);
;             PG8_BAR; PG8_WAIT_L(0); PG8_MMA(0, 1, At, B1); PG8_BAR;
;             PG8_LDA(At, 1, 1); PG8_STAGE(PG8_SA(1, 0), a3, voffA);
	s_add_u32 s52, s20, 0x80000
	s_addc_u32 s53, s21, 0
	s_add_i32 s55, s42, s29
	v_lshl_add_u64 v[142:143], s[52:53], 0, v[130:131]
	s_mov_b32 m0, s55
	s_nop 0
	global_load_lds_dwordx4 v[142:143], off
	v_lshl_add_u64 v[142:143], s[52:53], 0, v[128:129]
	s_add_i32 m0, s55, 0x2000
	s_nop 0
	global_load_lds_dwordx4 v[142:143], off
	s_waitcnt vmcnt(6)
	s_barrier
	s_setprio 1
	v_mfma_f32_16x16x32_bf16 v[52:55], v[198:201], v[166:169], v[52:55]
	v_mfma_f32_16x16x32_bf16 v[48:51], v[206:209], v[166:169], v[48:51]
	v_mfma_f32_16x16x32_bf16 v[36:39], v[198:201], v[174:177], v[36:39]
	v_mfma_f32_16x16x32_bf16 v[32:35], v[206:209], v[174:177], v[32:35]
	v_mfma_f32_16x16x32_bf16 v[20:23], v[198:201], v[182:185], v[20:23]
	v_mfma_f32_16x16x32_bf16 v[16:19], v[206:209], v[182:185], v[16:19]
	v_mfma_f32_16x16x32_bf16 v[4:7], v[198:201], v[190:193], v[4:7]
	v_mfma_f32_16x16x32_bf16 v[0:3], v[206:209], v[190:193], v[0:3]
	v_mfma_f32_16x16x32_bf16 v[52:55], v[202:205], v[170:173], v[52:55]
	v_mfma_f32_16x16x32_bf16 v[48:51], v[210:213], v[170:173], v[48:51]
	v_mfma_f32_16x16x32_bf16 v[36:39], v[202:205], v[178:181], v[36:39]
	v_mfma_f32_16x16x32_bf16 v[32:35], v[210:213], v[178:181], v[32:35]
	v_mfma_f32_16x16x32_bf16 v[20:23], v[202:205], v[186:189], v[20:23]
	v_mfma_f32_16x16x32_bf16 v[16:19], v[210:213], v[186:189], v[16:19]
	v_mfma_f32_16x16x32_bf16 v[4:7], v[202:205], v[194:197], v[4:7]
	v_mfma_f32_16x16x32_bf16 v[0:3], v[210:213], v[194:197], v[0:3]
	s_setprio 0
	s_add_i32 s52, 0, 0x18000
	v_add_u32_e32 v162, s52, v147
	s_barrier
	ds_read_b128 v[142:145], v162
	ds_read_b128 v[154:157], v162 offset:1024
	ds_read_b128 v[158:161], v162 offset:2048
	ds_read_b128 v[162:165], v162 offset:3072
	s_add_u32 s26, s26, 0x80000
	s_addc_u32 s27, s27, 0
	s_mov_b32 m0, s34
	v_lshl_add_u64 v[198:199], s[26:27], 0, v[130:131]
	ds_read_b128 v[166:169], v151 offset:32768
	ds_read_b128 v[170:173], v151 offset:33792
	ds_read_b128 v[174:177], v151 offset:34816
	ds_read_b128 v[178:181], v151 offset:35840
	ds_read_b128 v[182:185], v151 offset:36864
	ds_read_b128 v[186:189], v151 offset:37888
	ds_read_b128 v[190:193], v151 offset:38912
	ds_read_b128 v[194:197], v151 offset:39936
	global_load_lds_dwordx4 v[198:199], off
	v_lshl_add_u64 v[198:199], s[26:27], 0, v[128:129]
	s_mov_b32 m0, s35
	s_nop 0
	global_load_lds_dwordx4 v[198:199], off
	s_waitcnt lgkmcnt(8)
	s_barrier
	s_waitcnt lgkmcnt(0)
	s_setprio 1
	s_waitcnt lgkmcnt(0)
	v_mfma_f32_16x16x32_bf16 v[124:127], v[142:145], v[166:169], v[124:127]
	v_mfma_f32_16x16x32_bf16 v[120:123], v[158:161], v[166:169], v[120:123]
	v_mfma_f32_16x16x32_bf16 v[108:111], v[142:145], v[174:177], v[108:111]
	v_mfma_f32_16x16x32_bf16 v[104:107], v[158:161], v[174:177], v[104:107]
	v_mfma_f32_16x16x32_bf16 v[92:95], v[142:145], v[182:185], v[92:95]
	v_mfma_f32_16x16x32_bf16 v[88:91], v[158:161], v[182:185], v[88:91]
	v_mfma_f32_16x16x32_bf16 v[76:79], v[142:145], v[190:193], v[76:79]
	v_mfma_f32_16x16x32_bf16 v[72:75], v[158:161], v[190:193], v[72:75]
	v_mfma_f32_16x16x32_bf16 v[124:127], v[154:157], v[170:173], v[124:127]
	v_mfma_f32_16x16x32_bf16 v[120:123], v[162:165], v[170:173], v[120:123]
	v_mfma_f32_16x16x32_bf16 v[108:111], v[154:157], v[178:181], v[108:111]
	v_mfma_f32_16x16x32_bf16 v[104:107], v[162:165], v[178:181], v[104:107]
	v_mfma_f32_16x16x32_bf16 v[92:95], v[154:157], v[186:189], v[92:95]
	v_mfma_f32_16x16x32_bf16 v[88:91], v[162:165], v[186:189], v[88:91]
	v_mfma_f32_16x16x32_bf16 v[76:79], v[154:157], v[194:197], v[76:79]
	v_mfma_f32_16x16x32_bf16 v[72:75], v[162:165], v[194:197], v[72:75]
	s_setprio 0
	s_barrier
	s_add_i32 s26, 0, 0x1c000
	s_add_i32 s27, s52, s29
	v_add_u32_e32 v210, s26, v147
	v_lshl_add_u64 v[214:215], v[214:215], 0, s[6:7]
	s_mov_b32 m0, s27
	ds_read_b128 v[198:201], v210
	ds_read_b128 v[202:205], v210 offset:1024
	ds_read_b128 v[206:209], v210 offset:2048
	ds_read_b128 v[210:213], v210 offset:3072
	global_load_lds_dwordx4 v[214:215], off
	v_lshl_add_u64 v[214:215], v[216:217], 0, s[6:7]
	s_add_i32 m0, s27, 0x2000
	s_nop 0
	global_load_lds_dwordx4 v[214:215], off
	s_barrier
	s_waitcnt lgkmcnt(0)
	s_setprio 1
	s_waitcnt lgkmcnt(0)
	v_mfma_f32_16x16x32_bf16 v[116:119], v[198:201], v[166:169], v[116:119]
	v_mfma_f32_16x16x32_bf16 v[112:115], v[206:209], v[166:169], v[112:115]
	v_mfma_f32_16x16x32_bf16 v[100:103], v[198:201], v[174:177], v[100:103]
	v_mfma_f32_16x16x32_bf16 v[96:99], v[206:209], v[174:177], v[96:99]
	v_mfma_f32_16x16x32_bf16 v[84:87], v[198:201], v[182:185], v[84:87]
	v_mfma_f32_16x16x32_bf16 v[80:83], v[206:209], v[182:185], v[80:83]
	v_mfma_f32_16x16x32_bf16 v[68:71], v[198:201], v[190:193], v[68:71]
	v_mfma_f32_16x16x32_bf16 v[64:67], v[206:209], v[190:193], v[64:67]
	v_mfma_f32_16x16x32_bf16 v[116:119], v[202:205], v[170:173], v[116:119]
	v_mfma_f32_16x16x32_bf16 v[112:115], v[210:213], v[170:173], v[112:115]
	v_mfma_f32_16x16x32_bf16 v[100:103], v[202:205], v[178:181], v[100:103]
	v_mfma_f32_16x16x32_bf16 v[96:99], v[210:213], v[178:181], v[96:99]
	v_mfma_f32_16x16x32_bf16 v[84:87], v[202:205], v[186:189], v[84:87]
	v_mfma_f32_16x16x32_bf16 v[80:83], v[210:213], v[186:189], v[80:83]
	v_mfma_f32_16x16x32_bf16 v[68:71], v[202:205], v[194:197], v[68:71]
	v_mfma_f32_16x16x32_bf16 v[64:67], v[210:213], v[194:197], v[64:67]
	s_setprio 0
	s_mov_b32 m0, s39
	v_lshl_add_u64 v[214:215], v[218:219], 0, s[6:7]
	s_barrier
	ds_read_b128 v[166:169], v151 offset:49152
	ds_read_b128 v[170:173], v151 offset:50176
	ds_read_b128 v[174:177], v151 offset:51200
	ds_read_b128 v[178:181], v151 offset:52224
	ds_read_b128 v[182:185], v151 offset:53248
	ds_read_b128 v[186:189], v151 offset:54272
	ds_read_b128 v[190:193], v151 offset:55296
	ds_read_b128 v[194:197], v151 offset:56320
	global_load_lds_dwordx4 v[214:215], off
	v_lshl_add_u64 v[214:215], v[220:221], 0, s[6:7]
	s_mov_b32 m0, s40
	s_nop 0
	global_load_lds_dwordx4 v[214:215], off
	s_barrier
; #define PG8_STAGE(bufoff, gbase, voff) do { _Pragma("unroll") for (int _i = 0; _i < 2; ++_i) \
;         __builtin_amdgcn_global_load_lds((const unsigned*)((const char*)(gbase) + (voff)[_i]), (LAS unsigned*)(lds + (bufoff) + ldsw + _i * 8192), 16, 0, 0); } while (0)
; #define PG8_MMA(ai, bj, At, Bt) do { __builtin_amdgcn_s_setprio(1); _Pragma("unroll") for (int m = 0; m < 4; ++m) _Pragma("unroll") for (int n = 0; n < 2; ++n) _Pragma("unroll") for (int k = 0; k < 2; ++k) \
;         acc[ai][bj][m][n] = __builtin_amdgcn_mfma_f32_16x16x32_bf16(Bt[n][k], At[m][k], acc[ai][bj][m][n], 0, 0, 0); __builtin_amdgcn_s_setprio(0); } while (0)
; #define PG8_WAIT_V(n) asm volatile("s_waitcnt vmcnt(" #n ")" ::: "memory")
; #define PG8_WAIT_L(n) asm volatile("s_waitcnt lgkmcnt(" #n ")" ::: "memory")
; #define PG8_BAR __builtin_amdgcn_s_barrier()
; template <class Epi>
; __device__ __forceinline__ void gemm_phase(LAS unsigned char* lds, const Gemm g, const Order& S, const Epi& E, const int tid) {
;     ...
;             PG8_BAR; PG8_WAIT_L(0); PG8_MMA(1, 0, At, B0); PG8_BAR; PG8_SCHED;
;             PG8_STAGE(PG8_SB(1, 1), b3 + hstepB, voffB);
;             PG8_WAIT_V(6); PG8_BAR; PG8_MMA(1, 1, At, B1); PG8_BAR;
;     __device__ __forceinline__ void operator()(f32x4 (&acc)[2][2][4][2], const Unit& u, int wr, int wc, int fr, int fq) const {
;         const int row0 = u.pm * BM + wr * 64 + fr, col0 = u.pn * BM + wc * 32 + 4 * fq;
;         const int sec = u.pn >> 3;
;         const float scale = (sec == 0) ? 0.08838834764831845f : 1.0f;
; #pragma unroll
;         for (int ai = 0; ai < 2; ++ai)
; #pragma unroll
;             for (int m = 0; m < 4; ++m) {
;                 const int row = row0 + ai * HALF + m * 16;
;                 if (sec < 2 && wc == 0) {
;                     const f32x4 t0 = *(const f32x4*)(tab + (size_t)row * 32 + 8 * fq), t1 = *(const f32x4*)(tab + (size_t)row * 32 + 8 * fq + 4);
;                     const float cs[4] = {t0[0], t0[2], t1[0], t1[2]}, sn[4] = {t0[1], t0[3], t1[1], t1[3]};
; #pragma unroll
;                     for (int bj = 0; bj < 2; ++bj)
; #pragma unroll
;                         for (int j = 0; j < 4; ++j) { const float a = acc[ai][bj][m][0][j], b = acc[ai][bj][m][1][j];
;                             acc[ai][bj][m][0][j] = a * cs[j] - b * sn[j]; acc[ai][bj][m][1][j] = b * cs[j] + a * sn[j]; }
	s_waitcnt lgkmcnt(0)
	s_setprio 1
	s_waitcnt lgkmcnt(0)
	v_mfma_f32_16x16x32_bf16 v[60:63], v[142:145], v[166:169], v[60:63]
	v_mfma_f32_16x16x32_bf16 v[56:59], v[158:161], v[166:169], v[56:59]
	v_mfma_f32_16x16x32_bf16 v[44:47], v[142:145], v[174:177], v[44:47]
	v_mfma_f32_16x16x32_bf16 v[40:43], v[158:161], v[174:177], v[40:43]
	v_mfma_f32_16x16x32_bf16 v[28:31], v[142:145], v[182:185], v[28:31]
	v_mfma_f32_16x16x32_bf16 v[24:27], v[158:161], v[182:185], v[24:27]
	v_mfma_f32_16x16x32_bf16 v[12:15], v[142:145], v[190:193], v[12:15]
	v_mfma_f32_16x16x32_bf16 v[8:11], v[158:161], v[190:193], v[8:11]
	v_mfma_f32_16x16x32_bf16 v[60:63], v[154:157], v[170:173], v[60:63]
	v_mfma_f32_16x16x32_bf16 v[56:59], v[162:165], v[170:173], v[56:59]
	v_mfma_f32_16x16x32_bf16 v[44:47], v[154:157], v[178:181], v[44:47]
	v_mfma_f32_16x16x32_bf16 v[40:43], v[162:165], v[178:181], v[40:43]
	v_mfma_f32_16x16x32_bf16 v[28:31], v[154:157], v[186:189], v[28:31]
	v_mfma_f32_16x16x32_bf16 v[24:27], v[162:165], v[186:189], v[24:27]
	v_mfma_f32_16x16x32_bf16 v[12:15], v[154:157], v[194:197], v[12:15]
	v_mfma_f32_16x16x32_bf16 v[8:11], v[162:165], v[194:197], v[8:11]
	s_setprio 0
	s_barrier
	s_add_u32 s20, s20, 0x80080
	s_addc_u32 s21, s21, 0
	s_add_i32 s26, s26, s29
	v_lshl_add_u64 v[142:143], s[20:21], 0, v[130:131]
	s_mov_b32 m0, s26
	s_nop 0
	global_load_lds_dwordx4 v[142:143], off
	v_lshl_add_u64 v[142:143], s[20:21], 0, v[128:129]
	s_add_i32 m0, s26, 0x2000
	s_nop 0
	global_load_lds_dwordx4 v[142:143], off
	s_waitcnt vmcnt(6)
	s_barrier
	s_setprio 1
	v_mfma_f32_16x16x32_bf16 v[52:55], v[198:201], v[166:169], v[52:55]
	v_mfma_f32_16x16x32_bf16 v[48:51], v[206:209], v[166:169], v[48:51]
	v_mfma_f32_16x16x32_bf16 v[36:39], v[198:201], v[174:177], v[36:39]
	v_mfma_f32_16x16x32_bf16 v[32:35], v[206:209], v[174:177], v[32:35]
	v_mfma_f32_16x16x32_bf16 v[20:23], v[198:201], v[182:185], v[20:23]
	v_mfma_f32_16x16x32_bf16 v[16:19], v[206:209], v[182:185], v[16:19]
	v_mfma_f32_16x16x32_bf16 v[4:7], v[198:201], v[190:193], v[4:7]
	v_mfma_f32_16x16x32_bf16 v[0:3], v[206:209], v[190:193], v[0:3]
	v_mfma_f32_16x16x32_bf16 v[52:55], v[202:205], v[170:173], v[52:55]
	v_mfma_f32_16x16x32_bf16 v[48:51], v[210:213], v[170:173], v[48:51]
	v_mfma_f32_16x16x32_bf16 v[36:39], v[202:205], v[178:181], v[36:39]
	v_mfma_f32_16x16x32_bf16 v[32:35], v[210:213], v[178:181], v[32:35]
	v_mfma_f32_16x16x32_bf16 v[20:23], v[202:205], v[186:189], v[20:23]
	v_mfma_f32_16x16x32_bf16 v[16:19], v[210:213], v[186:189], v[16:19]
	v_mfma_f32_16x16x32_bf16 v[4:7], v[202:205], v[194:197], v[4:7]
	v_mfma_f32_16x16x32_bf16 v[0:3], v[210:213], v[194:197], v[0:3]
	s_setprio 0
	s_add_i32 s51, s51, 2
	s_add_u32 s18, s18, 0x100
	s_addc_u32 s19, s19, 0
	s_add_u32 s49, s49, 0x100
	s_addc_u32 s50, s50, 0
	s_cmp_gt_u32 s51, 29
	s_barrier
	s_cbranch_scc0 .LBB0_747
	s_cmp_lt_i32 s47, 16
	v_lshl_add_u32 v144, s4, 8, v146
	s_cselect_b64 s[4:5], -1, 0
	s_and_b64 s[18:19], s[8:9], s[4:5]
	v_cndmask_b32_e64 v142, 0, 1, s[18:19]
	v_cmp_ne_u32_e64 s[4:5], 1, v142
	s_andn2_b64 vcc, exec, s[18:19]
	v_ashrrev_i32_e32 v145, 31, v144
	s_cbranch_vccnz .LBB0_750
	v_lshlrev_b64 v[142:143], 7, v[144:145]
	v_lshl_add_u64 v[142:143], v[132:133], 0, v[142:143]
	global_load_dwordx4 v[178:181], v[142:143], off
	global_load_dwordx4 v[182:185], v[142:143], off offset:16
	global_load_dwordx4 v[186:189], v[142:143], off offset:2048
	global_load_dwordx4 v[190:193], v[142:143], off offset:2064
	s_movk_i32 s100, 0x1000
	s_mov_b32 s101, 0
	v_lshl_add_u64 v[242:243], v[142:143], 0, s[100:101]
	global_load_dwordx4 v[194:197], v[242:243], off
	global_load_dwordx4 v[198:201], v[242:243], off offset:16
	global_load_dwordx4 v[202:205], v[242:243], off offset:2048
	global_load_dwordx4 v[206:209], v[242:243], off offset:2064
	s_movk_i32 s100, 0x3000
	v_lshl_add_u64 v[242:243], v[242:243], 0, s[100:101]
	global_load_dwordx4 v[210:213], v[242:243], off
	global_load_dwordx4 v[214:217], v[242:243], off offset:16
	global_load_dwordx4 v[218:221], v[242:243], off offset:2048
	global_load_dwordx4 v[222:225], v[242:243], off offset:2064
	s_movk_i32 s100, 0x1000
	v_lshl_add_u64 v[242:243], v[242:243], 0, s[100:101]
	global_load_dwordx4 v[226:229], v[242:243], off
	global_load_dwordx4 v[230:233], v[242:243], off offset:16
	global_load_dwordx4 v[234:237], v[242:243], off offset:2048
	global_load_dwordx4 v[238:241], v[242:243], off offset:2064
	s_waitcnt vmcnt(14)
	v_mov_b32_e32 v154, v178
	v_mov_b32_e32 v155, v179
	v_mov_b32_e32 v156, v180
	v_mov_b32_e32 v157, v181
	v_mov_b32_e32 v158, v182
	v_mov_b32_e32 v159, v183
	v_mov_b32_e32 v160, v184
	v_mov_b32_e32 v161, v185
	v_mov_b32_e32 v142, v154
	v_mov_b32_e32 v143, v156
	v_mov_b32_e32 v156, v155
	v_mul_f32_e32 v154, v126, v158
	v_mul_f32_e32 v162, v122, v159
	v_mul_f32_e32 v164, v122, v158
	v_mul_f32_e32 v166, v126, v159
	v_mov_b32_e32 v122, v127
	v_mov_b32_e32 v126, v123
	v_mul_f32_e32 v168, v118, v158
	v_mul_f32_e32 v170, v114, v159
	v_mul_f32_e32 v158, v114, v158
	v_mul_f32_e32 v172, v118, v159
	v_mov_b32_e32 v114, v119
	v_mov_b32_e32 v118, v115
	v_pk_mul_f32 v[174:175], v[120:121], v[156:157]
	v_pk_mul_f32 v[120:121], v[120:121], v[142:143]
	v_pk_mul_f32 v[122:123], v[122:123], v[160:161]
	v_pk_mul_f32 v[126:127], v[126:127], v[160:161]
	v_pk_mul_f32 v[176:177], v[112:113], v[156:157]
	v_pk_mul_f32 v[114:115], v[114:115], v[160:161]
	v_pk_mul_f32 v[118:119], v[118:119], v[160:161]
	v_pk_mul_f32 v[112:113], v[112:113], v[142:143]
	v_mov_b32_e32 v155, v122
	v_mov_b32_e32 v163, v123
	v_pk_fma_f32 v[160:161], v[124:125], v[142:143], v[174:175] neg_lo:[0,0,1] neg_hi:[0,0,1]
	v_mov_b32_e32 v167, v127
	v_mov_b32_e32 v165, v126
	v_pk_fma_f32 v[120:121], v[124:125], v[156:157], v[120:121]
	v_mov_b32_e32 v169, v114
	v_mov_b32_e32 v171, v115
	v_pk_fma_f32 v[124:125], v[116:117], v[142:143], v[176:177] neg_lo:[0,0,1] neg_hi:[0,0,1]
	v_mov_b32_e32 v173, v119
	v_mov_b32_e32 v159, v118
	v_pk_fma_f32 v[112:113], v[116:117], v[156:157], v[112:113]
	v_pk_add_f32 v[126:127], v[154:155], v[162:163] neg_lo:[0,1] neg_hi:[0,1]
	v_pk_add_f32 v[122:123], v[166:167], v[164:165]
	v_pk_add_f32 v[118:119], v[168:169], v[170:171] neg_lo:[0,1] neg_hi:[0,1]
	v_pk_add_f32 v[114:115], v[172:173], v[158:159]
	v_mov_b32_e32 v116, v124
	v_mov_b32_e32 v117, v125
	v_mov_b32_e32 v124, v160
	v_mov_b32_e32 v125, v161
;     __device__ __forceinline__ void operator()(f32x4 (&acc)[2][2][4][2], const Unit& u, int wr, int wc, int fr, int fq) const {
;     ...
;                 const int row = row0 + ai * HALF + m * 16;
;                 if (sec < 2 && wc == 0) {
;                     const f32x4 t0 = *(const f32x4*)(tab + (size_t)row * 32 + 8 * fq), t1 = *(const f32x4*)(tab + (size_t)row * 32 + 8 * fq + 4);
;                     const float cs[4] = {t0[0], t0[2], t1[0], t1[2]}, sn[4] = {t0[1], t0[3], t1[1], t1[3]};
; #pragma unroll
;                     for (int bj = 0; bj < 2; ++bj)
; #pragma unroll
;                         for (int j = 0; j < 4; ++j) { const float a = acc[ai][bj][m][0][j], b = acc[ai][bj][m][1][j];
;                             acc[ai][bj][m][0][j] = a * cs[j] - b * sn[j]; acc[ai][bj][m][1][j] = b * cs[j] + a * sn[j]; }
;                 }
;                 bf16_t* rowp = O + (size_t)row * INC + col0;
; #pragma unroll
;                 for (int bj = 0; bj < 2; ++bj)
; #pragma unroll
;                     for (int n = 0; n < 2; ++n) { const f32x4 v = acc[ai][bj][m][n] * (scale * rt[u.i * 256 + wr * 64 + fr + ai * HALF + m * 16]); u32x2 w; w.x = pk2(v[0], v[1]); w.y = pk2(v[2], v[3]); *(u32x2*)(rowp + bj * HALF + n * 16) = w; }
.LBB0_750:
	s_cmp_lt_u32 s47, 8
	s_cselect_b64 vcc, -1, 0
	s_lshl_b32 s11, s46, 10
	v_add_u32_e32 v154, s11, v149
	ds_read_b32 v155, v154
	v_cndmask_b32_e32 v145, 1.0, v153, vcc
	v_lshl_or_b32 v142, s47, 8, v148
	v_mov_b64_e32 v[156:157], s[72:73]
	v_ashrrev_i32_e32 v143, 31, v142
	s_waitcnt lgkmcnt(0)
	v_mul_f32_e32 v158, v145, v155
	v_mad_i64_i32 v[156:157], s[18:19], v144, s43, v[156:157]
	v_pk_mul_f32 v[114:115], v[114:115], v[158:159] op_sel_hi:[1,0]
	v_pk_mul_f32 v[112:113], v[112:113], v[158:159] op_sel_hi:[1,0]
	v_lshl_add_u64 v[156:157], v[142:143], 1, v[156:157]
	v_cvt_pk_bf16_f32 v112, v112, v113
	v_cvt_pk_bf16_f32 v113, v114, v115
	v_pk_mul_f32 v[126:127], v[126:127], v[158:159] op_sel_hi:[1,0]
	v_pk_mul_f32 v[124:125], v[124:125], v[158:159] op_sel_hi:[1,0]
	v_pk_mul_f32 v[122:123], v[122:123], v[158:159] op_sel_hi:[1,0]
	v_pk_mul_f32 v[120:121], v[120:121], v[158:159] op_sel_hi:[1,0]
	v_pk_mul_f32 v[118:119], v[118:119], v[158:159] op_sel_hi:[1,0]
	v_pk_mul_f32 v[116:117], v[116:117], v[158:159] op_sel_hi:[1,0]
	global_store_dwordx2 v[156:157], v[112:113], off offset:288
	v_or_b32_e32 v112, 16, v144
	v_cvt_pk_bf16_f32 v124, v124, v125
	v_cvt_pk_bf16_f32 v125, v126, v127
	v_cvt_pk_bf16_f32 v120, v120, v121
	v_cvt_pk_bf16_f32 v121, v122, v123
	v_cvt_pk_bf16_f32 v116, v116, v117
	v_cvt_pk_bf16_f32 v117, v118, v119
	s_and_b64 vcc, exec, s[4:5]
	v_ashrrev_i32_e32 v113, 31, v112
	global_store_dwordx2 v[156:157], v[124:125], off
	global_store_dwordx2 v[156:157], v[120:121], off offset:32
	global_store_dwordx2 v[156:157], v[116:117], off offset:256
	s_cbranch_vccnz .LBB0_752
	s_waitcnt vmcnt(16)
	v_mov_b32_e32 v114, v186
	v_mov_b32_e32 v115, v187
	v_mov_b32_e32 v116, v188
	v_mov_b32_e32 v117, v189
	v_mov_b32_e32 v118, v190
	v_mov_b32_e32 v119, v191
	v_mov_b32_e32 v120, v192
	v_mov_b32_e32 v121, v193
	v_mov_b32_e32 v122, v114
	v_mov_b32_e32 v123, v116
	v_mov_b32_e32 v116, v115
	v_mul_f32_e32 v114, v110, v118
	v_mul_f32_e32 v124, v106, v119
	v_mul_f32_e32 v126, v106, v118
	v_mul_f32_e32 v156, v110, v119
	v_mov_b32_e32 v106, v111
	v_mov_b32_e32 v110, v107
	v_mul_f32_e32 v158, v102, v118
	v_mul_f32_e32 v160, v98, v119
	v_mul_f32_e32 v118, v98, v118
	v_mul_f32_e32 v162, v102, v119
	v_mov_b32_e32 v98, v103
	v_mov_b32_e32 v102, v99
	v_pk_mul_f32 v[164:165], v[104:105], v[116:117]
	v_pk_mul_f32 v[104:105], v[104:105], v[122:123]
	v_pk_mul_f32 v[106:107], v[106:107], v[120:121]
	v_pk_mul_f32 v[110:111], v[110:111], v[120:121]
	v_pk_mul_f32 v[166:167], v[96:97], v[116:117]
	v_pk_mul_f32 v[98:99], v[98:99], v[120:121]
	v_pk_mul_f32 v[102:103], v[102:103], v[120:121]
	v_pk_mul_f32 v[96:97], v[96:97], v[122:123]
	v_mov_b32_e32 v115, v106
	v_mov_b32_e32 v125, v107
	v_pk_fma_f32 v[120:121], v[108:109], v[122:123], v[164:165] neg_lo:[0,0,1] neg_hi:[0,0,1]
	v_mov_b32_e32 v157, v111
	v_mov_b32_e32 v127, v110
	v_pk_fma_f32 v[104:105], v[108:109], v[116:117], v[104:105]
	v_mov_b32_e32 v159, v98
	v_mov_b32_e32 v161, v99
	v_pk_fma_f32 v[108:109], v[100:101], v[122:123], v[166:167] neg_lo:[0,0,1] neg_hi:[0,0,1]
	v_mov_b32_e32 v163, v103
	v_mov_b32_e32 v119, v102
	v_pk_fma_f32 v[96:97], v[100:101], v[116:117], v[96:97]
	v_pk_add_f32 v[110:111], v[114:115], v[124:125] neg_lo:[0,1] neg_hi:[0,1]
	v_pk_add_f32 v[106:107], v[156:157], v[126:127]
	v_pk_add_f32 v[102:103], v[158:159], v[160:161] neg_lo:[0,1] neg_hi:[0,1]
	v_pk_add_f32 v[98:99], v[162:163], v[118:119]
	v_mov_b32_e32 v100, v108
	v_mov_b32_e32 v101, v109
	v_mov_b32_e32 v108, v120
	v_mov_b32_e32 v109, v121
.LBB0_752:
	ds_read_b32 v116, v154 offset:64
	v_mov_b64_e32 v[114:115], s[72:73]
	v_mad_i64_i32 v[112:113], s[18:19], v112, s43, v[114:115]
	v_lshl_add_u64 v[112:113], v[142:143], 1, v[112:113]
	s_waitcnt lgkmcnt(0)
	v_mul_f32_e32 v114, v145, v116
	v_pk_mul_f32 v[98:99], v[98:99], v[114:115] op_sel_hi:[1,0]
	v_pk_mul_f32 v[96:97], v[96:97], v[114:115] op_sel_hi:[1,0]
	v_pk_mul_f32 v[110:111], v[110:111], v[114:115] op_sel_hi:[1,0]
	v_cvt_pk_bf16_f32 v96, v96, v97
	v_cvt_pk_bf16_f32 v97, v98, v99
	v_pk_mul_f32 v[108:109], v[108:109], v[114:115] op_sel_hi:[1,0]
	v_pk_mul_f32 v[106:107], v[106:107], v[114:115] op_sel_hi:[1,0]
	v_pk_mul_f32 v[104:105], v[104:105], v[114:115] op_sel_hi:[1,0]
	v_pk_mul_f32 v[102:103], v[102:103], v[114:115] op_sel_hi:[1,0]
	v_pk_mul_f32 v[100:101], v[100:101], v[114:115] op_sel_hi:[1,0]
	global_store_dwordx2 v[112:113], v[96:97], off offset:288
	v_or_b32_e32 v96, 32, v144
	v_cvt_pk_bf16_f32 v108, v108, v109
	v_cvt_pk_bf16_f32 v109, v110, v111
	v_cvt_pk_bf16_f32 v104, v104, v105
	v_cvt_pk_bf16_f32 v105, v106, v107
	v_cvt_pk_bf16_f32 v100, v100, v101
	v_cvt_pk_bf16_f32 v101, v102, v103
	s_and_b64 vcc, exec, s[4:5]
	v_ashrrev_i32_e32 v97, 31, v96
	global_store_dwordx2 v[112:113], v[108:109], off
	global_store_dwordx2 v[112:113], v[104:105], off offset:32
	global_store_dwordx2 v[112:113], v[100:101], off offset:256
	s_cbranch_vccnz .LBB0_754
	s_waitcnt vmcnt(18)
	v_mov_b32_e32 v98, v194
	v_mov_b32_e32 v99, v195
	v_mov_b32_e32 v100, v196
	v_mov_b32_e32 v101, v197
	v_mov_b32_e32 v102, v198
	v_mov_b32_e32 v103, v199
	v_mov_b32_e32 v104, v200
	v_mov_b32_e32 v105, v201
	v_mov_b32_e32 v106, v98
	v_mov_b32_e32 v107, v100
	v_mov_b32_e32 v100, v99
	v_mul_f32_e32 v98, v94, v102
	v_mul_f32_e32 v108, v90, v103
	v_mul_f32_e32 v110, v90, v102
	v_mul_f32_e32 v112, v94, v103
	v_mov_b32_e32 v90, v95
	v_mov_b32_e32 v94, v91
	v_mul_f32_e32 v114, v86, v102
	v_mul_f32_e32 v116, v82, v103
	v_mul_f32_e32 v102, v82, v102
	v_mul_f32_e32 v118, v86, v103
	v_mov_b32_e32 v82, v87
	v_mov_b32_e32 v86, v83
	v_pk_mul_f32 v[120:121], v[88:89], v[100:101]
	v_pk_mul_f32 v[88:89], v[88:89], v[106:107]
	v_pk_mul_f32 v[90:91], v[90:91], v[104:105]
	v_pk_mul_f32 v[94:95], v[94:95], v[104:105]
	v_pk_mul_f32 v[122:123], v[80:81], v[100:101]
	v_pk_mul_f32 v[82:83], v[82:83], v[104:105]
	v_pk_mul_f32 v[86:87], v[86:87], v[104:105]
	v_pk_mul_f32 v[80:81], v[80:81], v[106:107]
	v_mov_b32_e32 v99, v90
	v_mov_b32_e32 v109, v91
	v_pk_fma_f32 v[104:105], v[92:93], v[106:107], v[120:121] neg_lo:[0,0,1] neg_hi:[0,0,1]
	v_mov_b32_e32 v113, v95
	v_mov_b32_e32 v111, v94
	v_pk_fma_f32 v[88:89], v[92:93], v[100:101], v[88:89]
	v_mov_b32_e32 v115, v82
	v_mov_b32_e32 v117, v83
	v_pk_fma_f32 v[92:93], v[84:85], v[106:107], v[122:123] neg_lo:[0,0,1] neg_hi:[0,0,1]
	v_mov_b32_e32 v119, v87
	v_mov_b32_e32 v103, v86
	v_pk_fma_f32 v[80:81], v[84:85], v[100:101], v[80:81]
	v_pk_add_f32 v[94:95], v[98:99], v[108:109] neg_lo:[0,1] neg_hi:[0,1]
	v_pk_add_f32 v[90:91], v[112:113], v[110:111]
	v_pk_add_f32 v[86:87], v[114:115], v[116:117] neg_lo:[0,1] neg_hi:[0,1]
	v_pk_add_f32 v[82:83], v[118:119], v[102:103]
	v_mov_b32_e32 v84, v92
	v_mov_b32_e32 v85, v93
	v_mov_b32_e32 v92, v104
	v_mov_b32_e32 v93, v105
;     __device__ __forceinline__ void operator()(f32x4 (&acc)[2][2][4][2], const Unit& u, int wr, int wc, int fr, int fq) const {
;     ...
;                 const int row = row0 + ai * HALF + m * 16;
;                 if (sec < 2 && wc == 0) {
;                     const f32x4 t0 = *(const f32x4*)(tab + (size_t)row * 32 + 8 * fq), t1 = *(const f32x4*)(tab + (size_t)row * 32 + 8 * fq + 4);
;                     const float cs[4] = {t0[0], t0[2], t1[0], t1[2]}, sn[4] = {t0[1], t0[3], t1[1], t1[3]};
; #pragma unroll
;                     for (int bj = 0; bj < 2; ++bj)
; #pragma unroll
;                         for (int j = 0; j < 4; ++j) { const float a = acc[ai][bj][m][0][j], b = acc[ai][bj][m][1][j];
;                             acc[ai][bj][m][0][j] = a * cs[j] - b * sn[j]; acc[ai][bj][m][1][j] = b * cs[j] + a * sn[j]; }
;                 }
;                 bf16_t* rowp = O + (size_t)row * INC + col0;
; #pragma unroll
;                 for (int bj = 0; bj < 2; ++bj)
; #pragma unroll
;                     for (int n = 0; n < 2; ++n) { const f32x4 v = acc[ai][bj][m][n] * (scale * rt[u.i * 256 + wr * 64 + fr + ai * HALF + m * 16]); u32x2 w; w.x = pk2(v[0], v[1]); w.y = pk2(v[2], v[3]); *(u32x2*)(rowp + bj * HALF + n * 16) = w; }
.LBB0_754:
	ds_read_b32 v100, v154 offset:128
	v_mov_b64_e32 v[98:99], s[72:73]
	v_mad_i64_i32 v[96:97], s[18:19], v96, s43, v[98:99]
	v_lshl_add_u64 v[96:97], v[142:143], 1, v[96:97]
	s_waitcnt lgkmcnt(0)
	v_mul_f32_e32 v98, v145, v100
	v_pk_mul_f32 v[82:83], v[82:83], v[98:99] op_sel_hi:[1,0]
	v_pk_mul_f32 v[80:81], v[80:81], v[98:99] op_sel_hi:[1,0]
	v_pk_mul_f32 v[94:95], v[94:95], v[98:99] op_sel_hi:[1,0]
	v_cvt_pk_bf16_f32 v80, v80, v81
	v_cvt_pk_bf16_f32 v81, v82, v83
	v_pk_mul_f32 v[92:93], v[92:93], v[98:99] op_sel_hi:[1,0]
	v_pk_mul_f32 v[90:91], v[90:91], v[98:99] op_sel_hi:[1,0]
	v_pk_mul_f32 v[88:89], v[88:89], v[98:99] op_sel_hi:[1,0]
	v_pk_mul_f32 v[86:87], v[86:87], v[98:99] op_sel_hi:[1,0]
	v_pk_mul_f32 v[84:85], v[84:85], v[98:99] op_sel_hi:[1,0]
	global_store_dwordx2 v[96:97], v[80:81], off offset:288
	v_or_b32_e32 v80, 48, v144
	v_cvt_pk_bf16_f32 v92, v92, v93
	v_cvt_pk_bf16_f32 v93, v94, v95
	v_cvt_pk_bf16_f32 v88, v88, v89
	v_cvt_pk_bf16_f32 v89, v90, v91
	v_cvt_pk_bf16_f32 v84, v84, v85
	v_cvt_pk_bf16_f32 v85, v86, v87
	s_and_b64 vcc, exec, s[4:5]
	v_ashrrev_i32_e32 v81, 31, v80
	global_store_dwordx2 v[96:97], v[92:93], off
	global_store_dwordx2 v[96:97], v[88:89], off offset:32
	global_store_dwordx2 v[96:97], v[84:85], off offset:256
	s_cbranch_vccnz .LBB0_756
	s_waitcnt vmcnt(20)
	v_mov_b32_e32 v82, v202
	v_mov_b32_e32 v83, v203
	v_mov_b32_e32 v84, v204
	v_mov_b32_e32 v85, v205
	v_mov_b32_e32 v86, v206
	v_mov_b32_e32 v87, v207
	v_mov_b32_e32 v88, v208
	v_mov_b32_e32 v89, v209
	v_mov_b32_e32 v90, v82
	v_mov_b32_e32 v91, v84
	v_mov_b32_e32 v84, v83
	v_mul_f32_e32 v82, v78, v86
	v_mul_f32_e32 v92, v74, v87
	v_mul_f32_e32 v94, v74, v86
	v_mul_f32_e32 v96, v78, v87
	v_mov_b32_e32 v74, v79
	v_mov_b32_e32 v78, v75
	v_mul_f32_e32 v98, v70, v86
	v_mul_f32_e32 v100, v66, v87
	v_mul_f32_e32 v86, v66, v86
	v_mul_f32_e32 v102, v70, v87
	v_mov_b32_e32 v66, v71
	v_mov_b32_e32 v70, v67
	v_pk_mul_f32 v[104:105], v[72:73], v[84:85]
	v_pk_mul_f32 v[72:73], v[72:73], v[90:91]
	v_pk_mul_f32 v[74:75], v[74:75], v[88:89]
	v_pk_mul_f32 v[78:79], v[78:79], v[88:89]
	v_pk_mul_f32 v[106:107], v[64:65], v[84:85]
	v_pk_mul_f32 v[66:67], v[66:67], v[88:89]
	v_pk_mul_f32 v[70:71], v[70:71], v[88:89]
	v_pk_mul_f32 v[64:65], v[64:65], v[90:91]
	v_mov_b32_e32 v83, v74
	v_mov_b32_e32 v93, v75
	v_pk_fma_f32 v[88:89], v[76:77], v[90:91], v[104:105] neg_lo:[0,0,1] neg_hi:[0,0,1]
	v_mov_b32_e32 v97, v79
	v_mov_b32_e32 v95, v78
	v_pk_fma_f32 v[72:73], v[76:77], v[84:85], v[72:73]
	v_mov_b32_e32 v99, v66
	v_mov_b32_e32 v101, v67
	v_pk_fma_f32 v[76:77], v[68:69], v[90:91], v[106:107] neg_lo:[0,0,1] neg_hi:[0,0,1]
	v_mov_b32_e32 v103, v71
	v_mov_b32_e32 v87, v70
	v_pk_fma_f32 v[64:65], v[68:69], v[84:85], v[64:65]
	v_pk_add_f32 v[78:79], v[82:83], v[92:93] neg_lo:[0,1] neg_hi:[0,1]
	v_pk_add_f32 v[74:75], v[96:97], v[94:95]
	v_pk_add_f32 v[70:71], v[98:99], v[100:101] neg_lo:[0,1] neg_hi:[0,1]
	v_pk_add_f32 v[66:67], v[102:103], v[86:87]
	v_mov_b32_e32 v68, v76
	v_mov_b32_e32 v69, v77
	v_mov_b32_e32 v76, v88
	v_mov_b32_e32 v77, v89
.LBB0_756:
	ds_read_b32 v84, v154 offset:192
	v_mov_b64_e32 v[82:83], s[72:73]
	v_mad_i64_i32 v[80:81], s[18:19], v80, s43, v[82:83]
	v_lshl_add_u64 v[80:81], v[142:143], 1, v[80:81]
	s_waitcnt lgkmcnt(0)
	v_mul_f32_e32 v82, v145, v84
	v_pk_mul_f32 v[66:67], v[66:67], v[82:83] op_sel_hi:[1,0]
	v_pk_mul_f32 v[64:65], v[64:65], v[82:83] op_sel_hi:[1,0]
	v_pk_mul_f32 v[78:79], v[78:79], v[82:83] op_sel_hi:[1,0]
	v_cvt_pk_bf16_f32 v64, v64, v65
	v_cvt_pk_bf16_f32 v65, v66, v67
	v_pk_mul_f32 v[76:77], v[76:77], v[82:83] op_sel_hi:[1,0]
	v_pk_mul_f32 v[74:75], v[74:75], v[82:83] op_sel_hi:[1,0]
	v_pk_mul_f32 v[72:73], v[72:73], v[82:83] op_sel_hi:[1,0]
	v_pk_mul_f32 v[70:71], v[70:71], v[82:83] op_sel_hi:[1,0]
	v_pk_mul_f32 v[68:69], v[68:69], v[82:83] op_sel_hi:[1,0]
	global_store_dwordx2 v[80:81], v[64:65], off offset:288
	v_add_u32_e32 v64, 0x80, v144
	v_cvt_pk_bf16_f32 v76, v76, v77
	v_cvt_pk_bf16_f32 v77, v78, v79
	v_cvt_pk_bf16_f32 v72, v72, v73
	v_cvt_pk_bf16_f32 v73, v74, v75
	v_cvt_pk_bf16_f32 v68, v68, v69
	v_cvt_pk_bf16_f32 v69, v70, v71
	s_and_b64 vcc, exec, s[4:5]
	v_ashrrev_i32_e32 v65, 31, v64
	global_store_dwordx2 v[80:81], v[76:77], off
	global_store_dwordx2 v[80:81], v[72:73], off offset:32
	global_store_dwordx2 v[80:81], v[68:69], off offset:256
	s_cbranch_vccnz .LBB0_758
	s_waitcnt vmcnt(22)
	v_mov_b32_e32 v66, v210
	v_mov_b32_e32 v67, v211
	v_mov_b32_e32 v68, v212
	v_mov_b32_e32 v69, v213
	v_mov_b32_e32 v70, v214
	v_mov_b32_e32 v71, v215
	v_mov_b32_e32 v72, v216
	v_mov_b32_e32 v73, v217
	v_mov_b32_e32 v74, v66
	v_mov_b32_e32 v75, v68
	v_mov_b32_e32 v68, v67
	v_mul_f32_e32 v66, v62, v70
	v_mul_f32_e32 v76, v58, v71
	v_mul_f32_e32 v78, v58, v70
	v_mul_f32_e32 v80, v62, v71
	v_mov_b32_e32 v58, v63
	v_mov_b32_e32 v62, v59
	v_mul_f32_e32 v82, v54, v70
	v_mul_f32_e32 v84, v50, v71
	v_mul_f32_e32 v70, v50, v70
	v_mul_f32_e32 v86, v54, v71
	v_mov_b32_e32 v50, v55
	v_mov_b32_e32 v54, v51
	v_pk_mul_f32 v[88:89], v[56:57], v[68:69]
	v_pk_mul_f32 v[56:57], v[56:57], v[74:75]
	v_pk_mul_f32 v[58:59], v[58:59], v[72:73]
	v_pk_mul_f32 v[62:63], v[62:63], v[72:73]
	v_pk_mul_f32 v[90:91], v[48:49], v[68:69]
	v_pk_mul_f32 v[50:51], v[50:51], v[72:73]
	v_pk_mul_f32 v[54:55], v[54:55], v[72:73]
	v_pk_mul_f32 v[48:49], v[48:49], v[74:75]
	v_mov_b32_e32 v67, v58
	v_mov_b32_e32 v77, v59
	v_pk_fma_f32 v[72:73], v[60:61], v[74:75], v[88:89] neg_lo:[0,0,1] neg_hi:[0,0,1]
	v_mov_b32_e32 v81, v63
	v_mov_b32_e32 v79, v62
	v_pk_fma_f32 v[56:57], v[60:61], v[68:69], v[56:57]
	v_mov_b32_e32 v83, v50
	v_mov_b32_e32 v85, v51
	v_pk_fma_f32 v[60:61], v[52:53], v[74:75], v[90:91] neg_lo:[0,0,1] neg_hi:[0,0,1]
	v_mov_b32_e32 v87, v55
	v_mov_b32_e32 v71, v54
	v_pk_fma_f32 v[48:49], v[52:53], v[68:69], v[48:49]
	v_pk_add_f32 v[62:63], v[66:67], v[76:77] neg_lo:[0,1] neg_hi:[0,1]
	v_pk_add_f32 v[58:59], v[80:81], v[78:79]
	v_pk_add_f32 v[54:55], v[82:83], v[84:85] neg_lo:[0,1] neg_hi:[0,1]
	v_pk_add_f32 v[50:51], v[86:87], v[70:71]
	v_mov_b32_e32 v52, v60
	v_mov_b32_e32 v53, v61
	v_mov_b32_e32 v60, v72
	v_mov_b32_e32 v61, v73
;     __device__ __forceinline__ void operator()(f32x4 (&acc)[2][2][4][2], const Unit& u, int wr, int wc, int fr, int fq) const {
;     ...
;                 const int row = row0 + ai * HALF + m * 16;
;                 if (sec < 2 && wc == 0) {
;                     const f32x4 t0 = *(const f32x4*)(tab + (size_t)row * 32 + 8 * fq), t1 = *(const f32x4*)(tab + (size_t)row * 32 + 8 * fq + 4);
;                     const float cs[4] = {t0[0], t0[2], t1[0], t1[2]}, sn[4] = {t0[1], t0[3], t1[1], t1[3]};
; #pragma unroll
;                     for (int bj = 0; bj < 2; ++bj)
; #pragma unroll
;                         for (int j = 0; j < 4; ++j) { const float a = acc[ai][bj][m][0][j], b = acc[ai][bj][m][1][j];
;                             acc[ai][bj][m][0][j] = a * cs[j] - b * sn[j]; acc[ai][bj][m][1][j] = b * cs[j] + a * sn[j]; }
;                 }
;                 bf16_t* rowp = O + (size_t)row * INC + col0;
; #pragma unroll
;                 for (int bj = 0; bj < 2; ++bj)
; #pragma unroll
;                     for (int n = 0; n < 2; ++n) { const f32x4 v = acc[ai][bj][m][n] * (scale * rt[u.i * 256 + wr * 64 + fr + ai * HALF + m * 16]); u32x2 w; w.x = pk2(v[0], v[1]); w.y = pk2(v[2], v[3]); *(u32x2*)(rowp + bj * HALF + n * 16) = w; }
.LBB0_758:
	ds_read_b32 v68, v154 offset:512
	v_mov_b64_e32 v[66:67], s[72:73]
	v_mad_i64_i32 v[64:65], s[18:19], v64, s43, v[66:67]
	v_lshl_add_u64 v[64:65], v[142:143], 1, v[64:65]
	s_waitcnt lgkmcnt(0)
	v_mul_f32_e32 v66, v145, v68
	v_pk_mul_f32 v[50:51], v[50:51], v[66:67] op_sel_hi:[1,0]
	v_pk_mul_f32 v[48:49], v[48:49], v[66:67] op_sel_hi:[1,0]
	v_pk_mul_f32 v[62:63], v[62:63], v[66:67] op_sel_hi:[1,0]
	v_cvt_pk_bf16_f32 v48, v48, v49
	v_cvt_pk_bf16_f32 v49, v50, v51
	v_pk_mul_f32 v[60:61], v[60:61], v[66:67] op_sel_hi:[1,0]
	v_pk_mul_f32 v[58:59], v[58:59], v[66:67] op_sel_hi:[1,0]
	v_pk_mul_f32 v[56:57], v[56:57], v[66:67] op_sel_hi:[1,0]
	v_pk_mul_f32 v[54:55], v[54:55], v[66:67] op_sel_hi:[1,0]
	v_pk_mul_f32 v[52:53], v[52:53], v[66:67] op_sel_hi:[1,0]
	global_store_dwordx2 v[64:65], v[48:49], off offset:288
	v_add_u32_e32 v48, 0x90, v144
	v_cvt_pk_bf16_f32 v60, v60, v61
	v_cvt_pk_bf16_f32 v61, v62, v63
	v_cvt_pk_bf16_f32 v56, v56, v57
	v_cvt_pk_bf16_f32 v57, v58, v59
	v_cvt_pk_bf16_f32 v52, v52, v53
	v_cvt_pk_bf16_f32 v53, v54, v55
	s_and_b64 vcc, exec, s[4:5]
	v_ashrrev_i32_e32 v49, 31, v48
	global_store_dwordx2 v[64:65], v[60:61], off
	global_store_dwordx2 v[64:65], v[56:57], off offset:32
	global_store_dwordx2 v[64:65], v[52:53], off offset:256
	s_cbranch_vccnz .LBB0_760
	s_waitcnt vmcnt(24)
	v_mov_b32_e32 v50, v218
	v_mov_b32_e32 v51, v219
	v_mov_b32_e32 v52, v220
	v_mov_b32_e32 v53, v221
	v_mov_b32_e32 v54, v222
	v_mov_b32_e32 v55, v223
	v_mov_b32_e32 v56, v224
	v_mov_b32_e32 v57, v225
	v_mov_b32_e32 v58, v50
	v_mov_b32_e32 v59, v52
	v_mov_b32_e32 v52, v51
	v_mul_f32_e32 v50, v46, v54
	v_mul_f32_e32 v60, v42, v55
	v_mul_f32_e32 v62, v42, v54
	v_mul_f32_e32 v64, v46, v55
	v_mov_b32_e32 v42, v47
	v_mov_b32_e32 v46, v43
	v_mul_f32_e32 v66, v38, v54
	v_mul_f32_e32 v68, v34, v55
	v_mul_f32_e32 v54, v34, v54
	v_mul_f32_e32 v70, v38, v55
	v_mov_b32_e32 v34, v39
	v_mov_b32_e32 v38, v35
	v_pk_mul_f32 v[72:73], v[40:41], v[52:53]
	v_pk_mul_f32 v[40:41], v[40:41], v[58:59]
	v_pk_mul_f32 v[42:43], v[42:43], v[56:57]
	v_pk_mul_f32 v[46:47], v[46:47], v[56:57]
	v_pk_mul_f32 v[74:75], v[32:33], v[52:53]
	v_pk_mul_f32 v[34:35], v[34:35], v[56:57]
	v_pk_mul_f32 v[38:39], v[38:39], v[56:57]
	v_pk_mul_f32 v[32:33], v[32:33], v[58:59]
	v_mov_b32_e32 v51, v42
	v_mov_b32_e32 v61, v43
	v_pk_fma_f32 v[56:57], v[44:45], v[58:59], v[72:73] neg_lo:[0,0,1] neg_hi:[0,0,1]
	v_mov_b32_e32 v65, v47
	v_mov_b32_e32 v63, v46
	v_pk_fma_f32 v[40:41], v[44:45], v[52:53], v[40:41]
	v_mov_b32_e32 v67, v34
	v_mov_b32_e32 v69, v35
	v_pk_fma_f32 v[44:45], v[36:37], v[58:59], v[74:75] neg_lo:[0,0,1] neg_hi:[0,0,1]
	v_mov_b32_e32 v71, v39
	v_mov_b32_e32 v55, v38
	v_pk_fma_f32 v[32:33], v[36:37], v[52:53], v[32:33]
	v_pk_add_f32 v[46:47], v[50:51], v[60:61] neg_lo:[0,1] neg_hi:[0,1]
	v_pk_add_f32 v[42:43], v[64:65], v[62:63]
	v_pk_add_f32 v[38:39], v[66:67], v[68:69] neg_lo:[0,1] neg_hi:[0,1]
	v_pk_add_f32 v[34:35], v[70:71], v[54:55]
	v_mov_b32_e32 v36, v44
	v_mov_b32_e32 v37, v45
	v_mov_b32_e32 v44, v56
	v_mov_b32_e32 v45, v57
;     __device__ __forceinline__ void operator()(f32x4 (&acc)[2][2][4][2], const Unit& u, int wr, int wc, int fr, int fq) const {
;     ...
;                 const int row = row0 + ai * HALF + m * 16;
;                 if (sec < 2 && wc == 0) {
;                     const f32x4 t0 = *(const f32x4*)(tab + (size_t)row * 32 + 8 * fq), t1 = *(const f32x4*)(tab + (size_t)row * 32 + 8 * fq + 4);
;                     const float cs[4] = {t0[0], t0[2], t1[0], t1[2]}, sn[4] = {t0[1], t0[3], t1[1], t1[3]};
; #pragma unroll
;                     for (int bj = 0; bj < 2; ++bj)
; #pragma unroll
;                         for (int j = 0; j < 4; ++j) { const float a = acc[ai][bj][m][0][j], b = acc[ai][bj][m][1][j];
;                             acc[ai][bj][m][0][j] = a * cs[j] - b * sn[j]; acc[ai][bj][m][1][j] = b * cs[j] + a * sn[j]; }
;                 }
;                 bf16_t* rowp = O + (size_t)row * INC + col0;
; #pragma unroll
;                 for (int bj = 0; bj < 2; ++bj)
; #pragma unroll
;                     for (int n = 0; n < 2; ++n) { const f32x4 v = acc[ai][bj][m][n] * (scale * rt[u.i * 256 + wr * 64 + fr + ai * HALF + m * 16]); u32x2 w; w.x = pk2(v[0], v[1]); w.y = pk2(v[2], v[3]); *(u32x2*)(rowp + bj * HALF + n * 16) = w; }
.LBB0_760:
	ds_read_b32 v52, v154 offset:576
	v_mov_b64_e32 v[50:51], s[72:73]
	v_mad_i64_i32 v[48:49], s[18:19], v48, s43, v[50:51]
	v_lshl_add_u64 v[48:49], v[142:143], 1, v[48:49]
	s_waitcnt lgkmcnt(0)
	v_mul_f32_e32 v50, v145, v52
	v_pk_mul_f32 v[34:35], v[34:35], v[50:51] op_sel_hi:[1,0]
	v_pk_mul_f32 v[32:33], v[32:33], v[50:51] op_sel_hi:[1,0]
	v_pk_mul_f32 v[46:47], v[46:47], v[50:51] op_sel_hi:[1,0]
	v_cvt_pk_bf16_f32 v32, v32, v33
	v_cvt_pk_bf16_f32 v33, v34, v35
	v_pk_mul_f32 v[44:45], v[44:45], v[50:51] op_sel_hi:[1,0]
	v_pk_mul_f32 v[42:43], v[42:43], v[50:51] op_sel_hi:[1,0]
	v_pk_mul_f32 v[40:41], v[40:41], v[50:51] op_sel_hi:[1,0]
	v_pk_mul_f32 v[38:39], v[38:39], v[50:51] op_sel_hi:[1,0]
	v_pk_mul_f32 v[36:37], v[36:37], v[50:51] op_sel_hi:[1,0]
	global_store_dwordx2 v[48:49], v[32:33], off offset:288
	v_add_u32_e32 v32, 0xa0, v144
	v_cvt_pk_bf16_f32 v44, v44, v45
	v_cvt_pk_bf16_f32 v45, v46, v47
	v_cvt_pk_bf16_f32 v40, v40, v41
	v_cvt_pk_bf16_f32 v41, v42, v43
	v_cvt_pk_bf16_f32 v36, v36, v37
	v_cvt_pk_bf16_f32 v37, v38, v39
	s_and_b64 vcc, exec, s[4:5]
	v_ashrrev_i32_e32 v33, 31, v32
	global_store_dwordx2 v[48:49], v[44:45], off
	global_store_dwordx2 v[48:49], v[40:41], off offset:32
	global_store_dwordx2 v[48:49], v[36:37], off offset:256
	s_cbranch_vccnz .LBB0_762
	s_waitcnt vmcnt(26)
	v_mov_b32_e32 v34, v226
	v_mov_b32_e32 v35, v227
	v_mov_b32_e32 v36, v228
	v_mov_b32_e32 v37, v229
	v_mov_b32_e32 v38, v230
	v_mov_b32_e32 v39, v231
	v_mov_b32_e32 v40, v232
	v_mov_b32_e32 v41, v233
	v_mov_b32_e32 v42, v34
	v_mov_b32_e32 v43, v36
	v_mov_b32_e32 v36, v35
	v_mul_f32_e32 v34, v30, v38
	v_mul_f32_e32 v44, v26, v39
	v_mul_f32_e32 v46, v26, v38
	v_mul_f32_e32 v48, v30, v39
	v_mov_b32_e32 v26, v31
	v_mov_b32_e32 v30, v27
	v_mul_f32_e32 v50, v22, v38
	v_mul_f32_e32 v52, v18, v39
	v_mul_f32_e32 v38, v18, v38
	v_mul_f32_e32 v54, v22, v39
	v_mov_b32_e32 v18, v23
	v_mov_b32_e32 v22, v19
	v_pk_mul_f32 v[56:57], v[24:25], v[36:37]
	v_pk_mul_f32 v[24:25], v[24:25], v[42:43]
	v_pk_mul_f32 v[26:27], v[26:27], v[40:41]
	v_pk_mul_f32 v[30:31], v[30:31], v[40:41]
	v_pk_mul_f32 v[58:59], v[16:17], v[36:37]
	v_pk_mul_f32 v[18:19], v[18:19], v[40:41]
	v_pk_mul_f32 v[22:23], v[22:23], v[40:41]
	v_pk_mul_f32 v[16:17], v[16:17], v[42:43]
	v_mov_b32_e32 v35, v26
	v_mov_b32_e32 v45, v27
	v_pk_fma_f32 v[40:41], v[28:29], v[42:43], v[56:57] neg_lo:[0,0,1] neg_hi:[0,0,1]
	v_mov_b32_e32 v49, v31
	v_mov_b32_e32 v47, v30
	v_pk_fma_f32 v[24:25], v[28:29], v[36:37], v[24:25]
	v_mov_b32_e32 v51, v18
	v_mov_b32_e32 v53, v19
	v_pk_fma_f32 v[28:29], v[20:21], v[42:43], v[58:59] neg_lo:[0,0,1] neg_hi:[0,0,1]
	v_mov_b32_e32 v55, v23
	v_mov_b32_e32 v39, v22
	v_pk_fma_f32 v[16:17], v[20:21], v[36:37], v[16:17]
	v_pk_add_f32 v[30:31], v[34:35], v[44:45] neg_lo:[0,1] neg_hi:[0,1]
	v_pk_add_f32 v[26:27], v[48:49], v[46:47]
	v_pk_add_f32 v[22:23], v[50:51], v[52:53] neg_lo:[0,1] neg_hi:[0,1]
	v_pk_add_f32 v[18:19], v[54:55], v[38:39]
	v_mov_b32_e32 v20, v28
	v_mov_b32_e32 v21, v29
	v_mov_b32_e32 v28, v40
	v_mov_b32_e32 v29, v41
.LBB0_762:
	ds_read_b32 v36, v154 offset:640
	v_mov_b64_e32 v[34:35], s[72:73]
	v_mad_i64_i32 v[32:33], s[18:19], v32, s43, v[34:35]
	v_lshl_add_u64 v[32:33], v[142:143], 1, v[32:33]
	s_waitcnt lgkmcnt(0)
	v_mul_f32_e32 v34, v145, v36
	v_pk_mul_f32 v[18:19], v[18:19], v[34:35] op_sel_hi:[1,0]
	v_pk_mul_f32 v[16:17], v[16:17], v[34:35] op_sel_hi:[1,0]
	v_pk_mul_f32 v[30:31], v[30:31], v[34:35] op_sel_hi:[1,0]
	v_cvt_pk_bf16_f32 v16, v16, v17
	v_cvt_pk_bf16_f32 v17, v18, v19
	v_pk_mul_f32 v[28:29], v[28:29], v[34:35] op_sel_hi:[1,0]
	v_pk_mul_f32 v[26:27], v[26:27], v[34:35] op_sel_hi:[1,0]
	v_pk_mul_f32 v[24:25], v[24:25], v[34:35] op_sel_hi:[1,0]
	v_pk_mul_f32 v[22:23], v[22:23], v[34:35] op_sel_hi:[1,0]
	v_pk_mul_f32 v[20:21], v[20:21], v[34:35] op_sel_hi:[1,0]
	global_store_dwordx2 v[32:33], v[16:17], off offset:288
	v_add_u32_e32 v16, 0xb0, v144
	v_cvt_pk_bf16_f32 v28, v28, v29
	v_cvt_pk_bf16_f32 v29, v30, v31
	v_cvt_pk_bf16_f32 v24, v24, v25
	v_cvt_pk_bf16_f32 v25, v26, v27
	v_cvt_pk_bf16_f32 v20, v20, v21
	v_cvt_pk_bf16_f32 v21, v22, v23
	s_and_b64 vcc, exec, s[4:5]
	v_ashrrev_i32_e32 v17, 31, v16
	global_store_dwordx2 v[32:33], v[28:29], off
	global_store_dwordx2 v[32:33], v[24:25], off offset:32
	global_store_dwordx2 v[32:33], v[20:21], off offset:256
	s_cbranch_vccnz .LBB0_743
	s_waitcnt vmcnt(28)
	v_mov_b32_e32 v18, v234
	v_mov_b32_e32 v19, v235
	v_mov_b32_e32 v20, v236
	v_mov_b32_e32 v21, v237
	v_mov_b32_e32 v22, v238
	v_mov_b32_e32 v23, v239
	v_mov_b32_e32 v24, v240
	v_mov_b32_e32 v25, v241
	v_mov_b32_e32 v26, v18
	v_mov_b32_e32 v27, v20
	v_mov_b32_e32 v20, v19
	v_mul_f32_e32 v18, v14, v22
	v_mul_f32_e32 v28, v10, v23
	v_mul_f32_e32 v30, v10, v22
	v_mul_f32_e32 v32, v14, v23
	v_mov_b32_e32 v10, v15
	v_mov_b32_e32 v14, v11
	v_mul_f32_e32 v34, v6, v22
	v_mul_f32_e32 v36, v2, v23
	v_mul_f32_e32 v22, v2, v22
	v_mul_f32_e32 v38, v6, v23
	v_mov_b32_e32 v2, v7
	v_mov_b32_e32 v6, v3
	v_pk_mul_f32 v[40:41], v[8:9], v[20:21]
	v_pk_mul_f32 v[8:9], v[8:9], v[26:27]
	v_pk_mul_f32 v[10:11], v[10:11], v[24:25]
	v_pk_mul_f32 v[14:15], v[14:15], v[24:25]
	v_pk_mul_f32 v[42:43], v[0:1], v[20:21]
	v_pk_mul_f32 v[2:3], v[2:3], v[24:25]
	v_pk_mul_f32 v[6:7], v[6:7], v[24:25]
	v_pk_mul_f32 v[0:1], v[0:1], v[26:27]
	v_mov_b32_e32 v19, v10
	v_mov_b32_e32 v29, v11
	v_pk_fma_f32 v[24:25], v[12:13], v[26:27], v[40:41] neg_lo:[0,0,1] neg_hi:[0,0,1]
	v_mov_b32_e32 v33, v15
	v_mov_b32_e32 v31, v14
	v_pk_fma_f32 v[8:9], v[12:13], v[20:21], v[8:9]
	v_mov_b32_e32 v35, v2
	v_mov_b32_e32 v37, v3
	v_pk_fma_f32 v[12:13], v[4:5], v[26:27], v[42:43] neg_lo:[0,0,1] neg_hi:[0,0,1]
	v_mov_b32_e32 v39, v7
	v_mov_b32_e32 v23, v6
	v_pk_fma_f32 v[0:1], v[4:5], v[20:21], v[0:1]
	v_pk_add_f32 v[14:15], v[18:19], v[28:29] neg_lo:[0,1] neg_hi:[0,1]
	v_pk_add_f32 v[10:11], v[32:33], v[30:31]
	v_pk_add_f32 v[6:7], v[34:35], v[36:37] neg_lo:[0,1] neg_hi:[0,1]
	v_pk_add_f32 v[2:3], v[38:39], v[22:23]
	v_mov_b32_e32 v4, v12
	v_mov_b32_e32 v5, v13
	v_mov_b32_e32 v12, v24
	v_mov_b32_e32 v13, v25
	s_branch .LBB0_743

; __global__ void __launch_bounds__(512, 2) mega(Params p, int ph_lo, int ph_hi) {
	.amdhsa_kernel _Z4mega6Paramsii
		.amdhsa_group_segment_fixed_size 0
		.amdhsa_private_segment_fixed_size 0
		.amdhsa_kernarg_size 440
		.amdhsa_user_sgpr_count 2
		.amdhsa_user_sgpr_dispatch_ptr 0
		.amdhsa_user_sgpr_queue_ptr 0
		.amdhsa_user_sgpr_kernarg_segment_ptr 1
		.amdhsa_user_sgpr_dispatch_id 0
		.amdhsa_user_sgpr_kernarg_preload_length 0
		.amdhsa_user_sgpr_kernarg_preload_offset 0
		.amdhsa_user_sgpr_private_segment_size 0
		.amdhsa_uses_dynamic_stack 0
		.amdhsa_enable_private_segment 0
		.amdhsa_system_sgpr_workgroup_id_x 1
		.amdhsa_system_sgpr_workgroup_id_y 0
		.amdhsa_system_sgpr_workgroup_id_z 0
		.amdhsa_system_sgpr_workgroup_info 0
		.amdhsa_system_vgpr_workitem_id 2
		.amdhsa_next_free_vgpr 256
		.amdhsa_next_free_sgpr 102
		.amdhsa_accum_offset 256
		.amdhsa_reserve_vcc 1
		.amdhsa_float_round_mode_32 0
		.amdhsa_float_round_mode_16_64 0
		.amdhsa_float_denorm_mode_32 3
		.amdhsa_float_denorm_mode_16_64 3
		.amdhsa_dx10_clamp 1
		.amdhsa_ieee_mode 1
		.amdhsa_fp16_overflow 0
		.amdhsa_tg_split 0
		.amdhsa_exception_fp_ieee_invalid_op 0
		.amdhsa_exception_fp_denorm_src 0
		.amdhsa_exception_fp_ieee_div_zero 0
		.amdhsa_exception_fp_ieee_overflow 0
		.amdhsa_exception_fp_ieee_underflow 0
		.amdhsa_exception_fp_ieee_inexact 0
		.amdhsa_exception_int_div_zero 0
	.end_amdhsa_kernel

; __global__ void __launch_bounds__(512, 2) mega(Params p, int ph_lo, int ph_hi) {
amdhsa.kernels:
  - .agpr_count:     0
    .args:
      - .offset:         0
        .size:           176
        .value_kind:     by_value
      - .offset:         176
        .size:           4
        .value_kind:     by_value
      - .offset:         180
        .size:           4
        .value_kind:     by_value
      - .offset:         184
        .size:           4
        .value_kind:     hidden_block_count_x
      - .offset:         188
        .size:           4
        .value_kind:     hidden_block_count_y
      - .offset:         192
        .size:           4
        .value_kind:     hidden_block_count_z
      - .offset:         196
        .size:           2
        .value_kind:     hidden_group_size_x
      - .offset:         198
        .size:           2
        .value_kind:     hidden_group_size_y
      - .offset:         200
        .size:           2
        .value_kind:     hidden_group_size_z
      - .offset:         202
        .size:           2
        .value_kind:     hidden_remainder_x
      - .offset:         204
        .size:           2
        .value_kind:     hidden_remainder_y
      - .offset:         206
        .size:           2
        .value_kind:     hidden_remainder_z
      - .offset:         224
        .size:           8
        .value_kind:     hidden_global_offset_x
      - .offset:         232
        .size:           8
        .value_kind:     hidden_global_offset_y
      - .offset:         240
        .size:           8
        .value_kind:     hidden_global_offset_z
      - .offset:         248
        .size:           2
        .value_kind:     hidden_grid_dims
      - .offset:         272
        .size:           8
        .value_kind:     hidden_multigrid_sync_arg
      - .offset:         304
        .size:           4
        .value_kind:     hidden_dynamic_lds_size
    .group_segment_fixed_size: 0
    .kernarg_segment_align: 8
    .kernarg_segment_size: 440
    .language:       OpenCL C
    .language_version:
      - 2
      - 0
    .max_flat_workgroup_size: 512
    .name:           _Z4mega6Paramsii
    .private_segment_fixed_size: 0
    .sgpr_count:     108
    .sgpr_spill_count: 35
    .symbol:         _Z4mega6Paramsii.kd
    .uniform_work_group_size: 1
    .uses_dynamic_stack: false
    .vgpr_count:     256
    .vgpr_spill_count: 0
    .wavefront_size: 64
